# attention: rope tables of the WG's query block + sink kept in LDS/VGPR (loop-invariant), no vmcnt waits in compute so K/V prefetch overlaps it; K, K-rope-table and Q row loads coalesced with per-wave
# speedup vs baseline: 1.0142x; 1.0142x over previous
.LBB0_337:
	s_cmp_lt_i32 s86, 3
	s_cselect_b64 s[0:1], -1, 0
	s_and_b64 s[88:89], s[0:1], s[6:7]
	s_waitcnt lgkmcnt(1)
	v_cndmask_b32_e64 v0, 0, 1, s[88:89]
	v_cmp_ne_u32_e64 s[68:69], 1, v0
	s_andn2_b64 vcc, exec, s[88:89]
	s_cbranch_vccnz .LBB0_410
	v_writelane_b32 v255, s88, 10
	s_cmpk_gt_i32 s97, 0x3ff
	v_readfirstlane_b32 s0, v251
	v_writelane_b32 v255, s89, 11
	v_writelane_b32 v255, s68, 12
	s_nop 1
	v_writelane_b32 v255, s69, 13
	s_cbranch_scc1 .LBB0_359
	s_lshl_b32 s56, s97, 12
	s_and_b32 s56, s56, 0x3c000
	s_add_u32 s58, s84, 0x80000
	s_addc_u32 s59, s85, 0
	s_add_u32 s58, s58, s56
	s_addc_u32 s59, s59, 0
	s_add_u32 s88, s58, 0x40000
	s_addc_u32 s89, s59, 0
	v_lshlrev_b32_e32 v14, 4, v251
	v_add_u32_e32 v15, 0x2000, v14
	global_load_dwordx4 v[16:19], v14, s[58:59]
	global_load_dwordx4 v[20:23], v15, s[58:59]
	global_load_dwordx4 v[24:27], v14, s[88:89]
	global_load_dwordx4 v[28:31], v15, s[88:89]
	s_and_b32 s56, s97, 3
	s_lshl_b32 s56, s56, 2
	v_lshrrev_b32_e32 v32, 1, v254
	v_add_lshl_u32 v32, v32, s56, 2
	global_load_dword v253, v32, s[80:81]
	v_bfe_u32 v33, v251, 2, 1
	v_and_b32_e32 v34, 1, v251
	v_lshlrev_b32_e32 v33, 2, v33
	v_lshl_or_b32 v33, v34, 1, v33
	v_bfe_u32 v34, v251, 8, 1
	v_or_b32_e32 v33, v33, v34
	v_cmp_ne_u32_e32 vcc, 0, v33
	v_mov_b32_e32 v35, 0x680
	v_cndmask_b32_e32 v35, 0, v35, vcc
	v_lshlrev_b32_e32 v33, 11, v33
	v_bfe_u32 v34, v251, 1, 1
	v_lshl_add_u32 v33, v34, 9, v33
	v_bfe_u32 v34, v251, 3, 5
	v_lshl_add_u32 v33, v34, 4, v33
	v_add_u32_e32 v33, 0x1b200, v33
	v_add_u32_e32 v35, v35, v33
	v_add_u32_e32 v35, 0x4000, v35
	v_and_b32_e32 v252, 0x7f, v251
	v_lshlrev_b32_e32 v252, 4, v252
	v_add_u32_e32 v252, 0x1b200, v252
	v_and_b32_e32 v250, 63, v251
	v_and_b32_e32 v248, 7, v250
	v_lshlrev_b32_e32 v248, 4, v248
	v_mov_b32_e32 v249, 0
	v_lshrrev_b32_e32 v250, 3, v250
	v_lshl_add_u32 v250, v254, 5, v250
	v_and_b32_e32 v10, 63, v251
	v_lshlrev_b32_e32 v10, 2, v10
	global_load_dword v11, v10, s[78:79]
	global_load_dword v12, v10, s[76:77]
	v_mov_b32_e32 v13, 0
	v_add_u32_e32 v13, 0x1b000, v13
	v_add_u32_e32 v10, v13, v10
	s_waitcnt vmcnt(0)
	ds_write_b128 v33, v[16:19]
	ds_write_b128 v33, v[20:23] offset:1024
	ds_write_b128 v35, v[24:27]
	ds_write_b128 v35, v[28:31] offset:1024
	ds_write_b32 v10, v11
	ds_write_b32 v10, v12 offset:256
	s_waitcnt lgkmcnt(0)
	s_lshl_b32 s96, s97, 5
	s_and_b32 s7, s96, 0x780
	v_mov_b32_e32 v80, 0
	v_lshrrev_b32_e32 v182, 1, v251
	s_addk_i32 s7, 0xff80
	v_mov_b32_e32 v82, v80
	v_mov_b32_e32 v83, v80
	v_add_u32_e32 v0, s7, v182
	v_mov_b32_e32 v81, v80
	v_mov_b64_e32 v[86:87], v[82:83]
	v_mov_b64_e32 v[94:95], v[82:83]
	v_mov_b64_e32 v[90:91], v[82:83]
	s_ashr_i32 s6, s97, 6
	s_and_b32 s1, s97, 3
	v_cmp_lt_i32_e32 vcc, -1, v0
	s_mov_b32 s5, 0
	v_mov_b64_e32 v[84:85], v[80:81]
	v_mov_b64_e32 v[92:93], v[80:81]
	v_mov_b64_e32 v[88:89], v[80:81]
	s_and_saveexec_b64 s[2:3], vcc
	s_cbranch_execz .LBB0_341
	v_readlane_b32 s8, v255, 6
	v_readlane_b32 s9, v255, 7
	v_add_u32_e32 v2, s7, v250
	v_lshl_add_u32 v2, s6, 11, v2
	s_movk_i32 s4, 0xc00
	v_mov_b64_e32 v[0:1], s[8:9]
	v_mad_i64_i32 v[0:1], s[8:9], v2, s4, v[0:1]
	s_lshl_b32 s4, s1, 7
	v_lshl_add_u64 v[0:1], v[0:1], 0, s[4:5]
	v_lshl_add_u64 v[0:1], v[0:1], 0, v[248:249]
	s_movk_i32 s4, 0x6000
	global_load_dwordx4 v[80:83], v[0:1], off offset:2048
	v_lshl_add_u64 v[0:1], v[0:1], 0, s[4:5]
	global_load_dwordx4 v[84:87], v[0:1], off offset:2048
	v_lshl_add_u64 v[0:1], v[0:1], 0, s[4:5]
	global_load_dwordx4 v[88:91], v[0:1], off offset:2048
	v_lshl_add_u64 v[0:1], v[0:1], 0, s[4:5]
	global_load_dwordx4 v[92:95], v[0:1], off offset:2048

.LBB0_345:
	s_or_b64 exec, exec, s[2:3]
	v_mbcnt_lo_u32_b32 v0, -1, 0
	v_mbcnt_hi_u32_b32 v4, -1, v0
	v_and_b32_e32 v1, 64, v4
	v_xor_b32_e32 v0, 1, v4
	v_add_u32_e32 v5, 64, v1
	v_bfe_u32 v3, v251, 5, 1
	v_cmp_lt_i32_e32 vcc, v0, v5
	v_xor_b32_e32 v10, 32, v4
	v_and_b32_e32 v184, 31, v251
	v_cndmask_b32_e32 v0, v4, v0, vcc
	v_cmp_lt_i32_e32 vcc, v10, v5
	v_lshlrev_b32_e32 v5, 2, v3
	v_or_b32_e32 v16, 2, v5
	v_cmp_gt_u32_e64 s[6:7], v16, v184
	v_or_b32_e32 v16, 3, v5
	s_add_u32 s82, s84, 0x80000
	v_cmp_gt_u32_e64 s[8:9], v16, v184
	v_or_b32_e32 v16, 8, v5
	s_addc_u32 s83, s85, 0
	v_cmp_gt_u32_e64 s[10:11], v16, v184
	v_or_b32_e32 v16, 9, v5
	s_add_u32 s92, s84, 0xc0000
	v_cmp_gt_u32_e64 s[12:13], v16, v184
	v_or_b32_e32 v16, 10, v5
	s_addc_u32 s93, s85, 0
	s_lshr_b32 s1, s0, 7
	s_and_b32 s91, s0, 64
	s_movk_i32 s0, 0x90
	v_cmp_gt_u32_e64 s[14:15], v16, v184
	v_or_b32_e32 v16, 11, v5
	v_mad_u32_u24 v6, v182, s0, 0
	s_movk_i32 s0, 0x208
	v_cmp_gt_u32_e64 s[16:17], v16, v184
	v_or_b32_e32 v16, 16, v5
	v_lshlrev_b32_e32 v96, 4, v3
	v_mad_u32_u24 v9, v120, s0, 0
	v_cndmask_b32_e32 v4, v4, v10, vcc
	s_lshr_b32 s0, s91, 5
	v_cmp_gt_u32_e64 s[18:19], v16, v184
	v_or_b32_e32 v16, 17, v5
	v_writelane_b32 v255, s1, 14
	v_lshlrev_b32_e32 v126, 3, v3
	v_lshlrev_b32_e32 v188, 2, v4
	v_add_u32_e32 v4, 0, v96
	s_or_b32 s1, s0, 1
	s_add_i32 s33, s0, 2
	s_add_i32 s54, s0, 3
	s_or_b32 s0, s0, 4
	v_cmp_gt_u32_e64 s[20:21], v16, v184
	v_or_b32_e32 v16, 18, v5
	v_sub_u32_e32 v10, v4, v126
	v_cmp_gt_u32_e64 s[22:23], v16, v184
	v_or_b32_e32 v16, 19, v5
	s_cmp_eq_u32 s91, 0
	v_readlane_b32 s2, v255, 6
	v_lshl_or_b32 v15, s0, 5, v184
	v_cmp_gt_u32_e64 s[24:25], v16, v184
	v_or_b32_e32 v16, 24, v5
	s_cselect_b64 s[36:37], -1, 0
	v_lshl_add_u32 v20, s0, 6, v10
	s_or_b32 s0, s91, 32
	v_mov_b32_e32 v127, v97
	v_readlane_b32 s3, v255, 7
	v_lshl_or_b32 v12, s1, 5, v184
	v_cmp_gt_u32_e64 s[26:27], v16, v184
	v_or_b32_e32 v16, 25, v5
	v_lshl_add_u32 v17, s1, 6, v10
	s_lshr_b32 s1, s0, 5
	v_lshl_add_u64 v[134:135], s[2:3], 0, v[96:97]
	v_lshl_add_u64 v[146:147], s[2:3], 0, v[126:127]
	v_lshl_or_b32 v13, s33, 5, v184
	v_lshl_or_b32 v14, s54, 5, v184
	v_cmp_gt_u32_e64 s[2:3], v5, v184
	v_cmp_lt_u32_e64 s[4:5], v5, v184
	v_cmp_gt_u32_e64 s[28:29], v16, v184
	v_or_b32_e32 v16, 26, v5
	v_or_b32_e32 v5, 27, v5
	v_lshl_add_u32 v18, s33, 6, v10
	v_lshl_add_u32 v19, s54, 6, v10
	s_add_i32 s33, s1, 1
	s_add_i32 s54, s1, 2
	s_add_i32 s55, s1, 3
	s_or_b32 s1, s1, 4
	v_writelane_b32 v255, s0, 15
	v_and_b32_e32 v2, 1, v251
	v_cmp_gt_u32_e64 s[34:35], v5, v184
	v_lshl_add_u32 v5, s91, 1, v10
	v_or_b32_e32 v21, s0, v184
	v_lshl_or_b32 v25, s1, 5, v184
	v_lshl_add_u32 v26, s0, 1, v10
	v_lshl_add_u32 v27, s33, 6, v10
	v_lshl_add_u32 v28, s54, 6, v10
	v_lshl_add_u32 v29, s55, 6, v10
	v_lshl_add_u32 v10, s1, 6, v10
	v_readlane_b32 s0, v255, 1
	v_or_b32_e32 v185, s91, v184
	v_lshlrev_b32_e32 v187, 2, v0
	v_lshlrev_b32_e32 v0, 6, v2
	v_lshlrev_b32_e32 v7, 5, v2
	v_lshlrev_b32_e32 v2, 4, v251
	v_lshl_or_b32 v22, s33, 5, v184
	v_lshl_or_b32 v23, s54, 5, v184
	v_lshl_or_b32 v24, s55, 5, v184
	v_readlane_b32 s1, v255, 2
	v_mov_b32_e32 v1, v97
	v_and_b32_e32 v8, 0x3fc, v251
	v_and_b32_e32 v2, 16, v2
	v_mul_u32_u24_e32 v11, 0x90, v185
	v_mul_u32_u24_e32 v12, 0x90, v12
	v_mul_u32_u24_e32 v13, 0x90, v13
	v_mul_u32_u24_e32 v14, 0x90, v14
	v_mul_u32_u24_e32 v15, 0x90, v15
	v_cmp_gt_u32_e64 s[30:31], v16, v184
	v_mul_u32_u24_e32 v16, 0x208, v184
	v_mul_u32_u24_e32 v21, 0x90, v21
	v_mul_u32_u24_e32 v22, 0x90, v22
	v_mul_u32_u24_e32 v23, 0x90, v23
	v_mul_u32_u24_e32 v24, 0x90, v24
	v_mul_u32_u24_e32 v25, 0x90, v25
	v_lshlrev_b32_e32 v96, 5, v3
	s_lshl_b32 s1, s0, 5
	s_lshl_b32 s0, s0, 2
	v_add_u32_e32 v186, 0xffffff80, v182
	s_mov_b32 s95, 0
	v_lshl_add_u64 v[142:143], s[82:83], 0, v[0:1]
	v_lshl_add_u64 v[144:145], s[92:93], 0, v[0:1]
	v_or_b32_e32 v127, 16, v126
	v_lshl_add_u64 v[148:149], s[78:79], 0, v[0:1]
	v_lshl_add_u64 v[150:151], s[76:77], 0, v[96:97]
	v_mov_b32_e32 v242, 0
	v_add_u32_e32 v242, 0x1b000, v242
	v_add_u32_e32 v243, v242, v96
	v_add_u32_e32 v243, 0x100, v243
	v_add_u32_e32 v242, v242, v0
	s_lshl_b32 s90, s97, 2
	v_writelane_b32 v255, s0, 16
	s_movk_i32 s65, 0xc00
	s_mov_b32 s54, 0xffff0000
	v_mov_b32_e32 v189, 0x358637bd
	v_add_u32_e32 v190, v6, v7
	v_add_u32_e32 v191, v9, v8
	v_lshlrev_b32_e32 v152, 1, v2
	v_add_u32_e32 v192, v4, v11
	v_add_u32_e32 v193, v4, v12
	v_add_u32_e32 v194, v4, v13
	v_add_u32_e32 v195, v4, v14
	v_add_u32_e32 v196, v4, v15
	v_add_u32_e32 v197, v5, v16
	v_add_u32_e32 v198, v17, v16
	v_add_u32_e32 v199, v18, v16
	v_add_u32_e32 v200, v19, v16
	v_add_u32_e32 v201, v20, v16
	v_add_u32_e32 v202, v4, v21
	v_add_u32_e32 v203, v4, v22
	v_add_u32_e32 v204, v4, v23
	v_add_u32_e32 v205, v4, v24
	v_add_u32_e32 v206, v4, v25
	v_add_u32_e32 v207, v26, v16
	v_add_u32_e32 v208, v27, v16
	v_add_u32_e32 v209, v28, v16
	v_add_u32_e32 v210, v29, v16
	v_add_u32_e32 v211, v10, v16
	v_mov_b32_e32 v212, 0xff800000
	s_mov_b32 s33, s97
	s_branch .LBB0_348

.LBB0_348:
	ds_read_b128 v[24:27], v242 offset:16
	ds_read_b128 v[28:31], v242 offset:144
	s_bfe_u32 s88, s33, 0x40002
	s_lshl_b32 s68, s88, 7
	v_add_u32_e32 v0, s68, v186
	v_max_i32_e32 v0, 0, v0
	v_lshlrev_b32_e32 v96, 7, v0
	v_lshl_add_u64 v[48:49], v[142:143], 0, v[96:97]
	v_lshl_add_u64 v[98:99], v[144:145], 0, v[96:97]
	s_add_i32 s58, s68, 0xffffff80
	v_add_u32_e32 v230, s58, v250
	v_lshl_add_u32 v230, v230, 7, v248
	v_max_i32_e32 v231, v248, v230
	global_load_dwordx4 v[116:119], v231, s[82:83]
	global_load_dwordx4 v[154:157], v231, s[92:93]
	v_add_u32_e32 v230, 0x400, v230
	v_max_i32_e32 v231, v248, v230
	global_load_dwordx4 v[44:47], v231, s[82:83]
	global_load_dwordx4 v[68:71], v231, s[92:93]
	v_add_u32_e32 v230, 0x400, v230
	v_max_i32_e32 v231, v248, v230
	global_load_dwordx4 v[158:161], v231, s[82:83]
	global_load_dwordx4 v[162:165], v231, s[92:93]
	v_add_u32_e32 v230, 0x400, v230
	v_max_i32_e32 v231, v248, v230
	global_load_dwordx4 v[40:43], v231, s[82:83]
	global_load_dwordx4 v[48:51], v231, s[92:93]
	ds_read_b128 v[72:75], v242
	ds_read_b128 v[16:19], v242 offset:48
	ds_read_b128 v[32:35], v242 offset:32
	ds_read_b128 v[20:23], v242 offset:176
	ds_read_b128 v[36:39], v242 offset:160
	ds_read_b128 v[76:79], v242 offset:128
	s_mov_b32 s0, s97
	s_and_b32 s97, s90, 12
	s_and_b32 s89, s96, 0xfffff800
	v_readlane_b32 s55, v255, 14
	s_waitcnt vmcnt(16)
	v_and_b32_e32 v224, 63, v251
	v_lshrrev_b32_e32 v225, 3, v224
	s_movk_i32 s58, 0x90
	v_mul_u32_u24_e32 v226, 0x1200, v254
	v_add_u32_e32 v226, 0x12000, v226
	v_and_b32_e32 v227, 7, v224
	v_lshlrev_b32_e32 v227, 4, v227
	v_mad_u32_u24 v227, v225, s58, v227
	v_add_u32_e32 v227, v227, v226
	v_lshrrev_b32_e32 v225, 1, v224
	v_and_b32_e32 v224, 1, v224
	v_lshlrev_b32_e32 v224, 5, v224
	v_mad_u32_u24 v224, v225, s58, v224
	v_add_u32_e32 v224, v224, v226
	ds_write_b128 v227, v[80:83]
	ds_write_b128 v227, v[84:87] offset:1152
	ds_write_b128 v227, v[88:91] offset:2304
	ds_write_b128 v227, v[92:95] offset:3456
	s_waitcnt lgkmcnt(0)
	ds_read_b128 v[80:83], v224
	ds_read_b128 v[84:87], v224 offset:16
	ds_read_b128 v[92:95], v224 offset:64
	ds_read_b128 v[88:91], v224 offset:80
	s_waitcnt lgkmcnt(0)
	v_and_b32_e32 v64, 0xffff0000, v84
	v_lshlrev_b32_e32 v65, 16, v84
	v_and_b32_e32 v60, 0xffff0000, v85
	v_lshlrev_b32_e32 v61, 16, v85
	s_add_i32 s97, s97, s55
	v_or_b32_e32 v8, s89, v185
	v_and_b32_e32 v66, 0xffff0000, v88
	v_lshlrev_b32_e32 v67, 16, v88
	v_and_b32_e32 v62, 0xffff0000, v89
	v_lshlrev_b32_e32 v63, 16, v89
	v_pk_mul_f32 v[0:1], v[64:65], v[64:65]
	v_pk_mul_f32 v[2:3], v[60:61], v[60:61]
	v_or_b32_e32 v8, s68, v8
	s_lshl_b32 s94, s97, 7
	v_and_b32_e32 v56, 0xffff0000, v86
	v_lshlrev_b32_e32 v57, 16, v86
	v_and_b32_e32 v52, 0xffff0000, v87
	v_lshlrev_b32_e32 v53, 16, v87
	v_pk_fma_f32 v[214:215], v[66:67], v[66:67], v[0:1]
	v_pk_fma_f32 v[216:217], v[62:63], v[62:63], v[2:3]
	v_lshl_add_u64 v[0:1], v[134:135], 0, s[94:95]
	v_or_b32_e32 v2, 32, v8
	v_and_b32_e32 v58, 0xffff0000, v90
	v_lshlrev_b32_e32 v59, 16, v90
	v_and_b32_e32 v54, 0xffff0000, v91
	v_lshlrev_b32_e32 v55, 16, v91
	v_pk_mul_f32 v[4:5], v[56:57], v[56:57]
	v_pk_mul_f32 v[6:7], v[52:53], v[52:53]
	v_pk_fma_f32 v[218:219], v[58:59], v[58:59], v[4:5]
	v_pk_fma_f32 v[220:221], v[54:55], v[54:55], v[6:7]
	v_readlane_b32 s78, v255, 6
	v_readlane_b32 s79, v255, 7
	s_or_b32 s58, s89, s68
	s_or_b32 s58, s58, s91
	v_and_b32_e32 v231, 7, v250
	v_add_u32_e32 v231, s58, v231
	v_add_u32_e32 v230, s94, v248
	v_mad_u32_u24 v230, v231, s65, v230
	s_nop 0
	global_load_dwordx4 v[0:3], v230, s[78:79]
	v_add_u32_e32 v230, 0x6000, v230
	global_load_dwordx4 v[4:7], v230, s[78:79]
	v_add_u32_e32 v230, 0x6000, v230
	global_load_dwordx4 v[8:11], v230, s[78:79]
	v_add_u32_e32 v230, 0x6000, v230
	global_load_dwordx4 v[12:15], v230, s[78:79]
	v_add_u32_e32 v230, 0x6000, v230
	global_load_dwordx4 v[100:103], v230, s[78:79]
	v_add_u32_e32 v230, 0x6000, v230
	global_load_dwordx4 v[104:107], v230, s[78:79]
	v_add_u32_e32 v230, 0x6000, v230
	global_load_dwordx4 v[108:111], v230, s[78:79]
	v_add_u32_e32 v230, 0x6000, v230
	global_load_dwordx4 v[112:115], v230, s[78:79]
	v_lshlrev_b32_e32 v239, 16, v92
	v_lshlrev_b32_e32 v238, 16, v80
	v_and_b32_e32 v245, 0xffff0000, v92
	v_and_b32_e32 v244, 0xffff0000, v80
	v_lshlrev_b32_e32 v229, 16, v93
	v_lshlrev_b32_e32 v228, 16, v81
	v_pk_mul_f32 v[240:241], v[238:239], v[238:239]
	v_pk_mul_f32 v[246:247], v[244:245], v[244:245]
	v_pk_mul_f32 v[230:231], v[228:229], v[228:229]
	v_and_b32_e32 v235, 0xffff0000, v93
	v_and_b32_e32 v234, 0xffff0000, v81
	v_lshlrev_b32_e32 v171, 16, v94
	v_lshlrev_b32_e32 v170, 16, v82
	v_pk_mul_f32 v[236:237], v[234:235], v[234:235]
	v_and_b32_e32 v173, 0xffff0000, v94
	v_and_b32_e32 v172, 0xffff0000, v82
	v_pk_mul_f32 v[178:179], v[170:171], v[170:171]
	v_lshlrev_b32_e32 v167, 16, v95
	v_lshlrev_b32_e32 v166, 16, v83
	v_pk_mul_f32 v[180:181], v[172:173], v[172:173]
	v_and_b32_e32 v169, 0xffff0000, v95
	v_and_b32_e32 v168, 0xffff0000, v83
	v_pk_mul_f32 v[174:175], v[166:167], v[166:167]
	v_pk_mul_f32 v[176:177], v[168:169], v[168:169]
	v_readlane_b32 s76, v255, 1
	s_add_i32 s33, s33, s76
	v_readlane_b32 s77, v255, 2
	s_cmpk_gt_i32 s33, 0x3ff
	s_cselect_b64 s[76:77], -1, 0
	s_waitcnt lgkmcnt(0)
	v_mov_b32_e32 v98, v26
	s_waitcnt lgkmcnt(0)
	v_mov_b32_e32 v223, v28
	v_add_f32_e32 v26, v247, v246
	v_add_f32_e32 v28, v241, v240
	v_add_f32_e32 v26, v28, v26
	v_add_f32_e32 v28, v231, v230
	v_mov_b32_e32 v222, v24
	v_add_f32_e32 v24, v237, v236
	v_add_f32_e32 v26, v28, v26
	v_add_f32_e32 v24, v24, v26
	v_add_f32_e32 v26, v179, v178
	v_add_f32_e32 v24, v26, v24
	v_add_f32_e32 v26, v181, v180
	v_add_f32_e32 v24, v26, v24
	v_add_f32_e32 v26, v175, v174
	v_add_f32_e32 v24, v26, v24
	v_add_f32_e32 v26, v177, v176
	v_add_f32_e32 v24, v26, v24
	v_add_f32_e32 v24, v215, v24
	v_add_f32_e32 v24, v214, v24
	v_add_f32_e32 v24, v217, v24
	v_add_f32_e32 v24, v216, v24
	v_add_f32_e32 v24, v219, v24
	v_add_f32_e32 v24, v218, v24
	v_add_f32_e32 v24, v221, v24
	v_add_f32_e32 v24, v220, v24
	ds_bpermute_b32 v26, v187, v24
	s_waitcnt vmcnt(8)
	ds_write_b128 v227, v[116:119]
	ds_write_b128 v227, v[44:47] offset:1152
	ds_write_b128 v227, v[158:161] offset:2304
	ds_write_b128 v227, v[40:43] offset:3456
	v_and_b32_e32 v225, 63, v251
	v_lshrrev_b32_e32 v224, 1, v225
	v_and_b32_e32 v225, 1, v225
	v_lshlrev_b32_e32 v225, 6, v225
	v_mul_u32_u24_e32 v224, 0x90, v224
	v_add3_u32 v225, v224, v225, v226
	s_waitcnt lgkmcnt(0)
	ds_read_b128 v[116:119], v225
	ds_read_b128 v[44:47], v225 offset:16
	ds_read_b128 v[158:161], v225 offset:32
	ds_read_b128 v[40:43], v225 offset:48
	s_waitcnt lgkmcnt(0)
	ds_write_b128 v227, v[154:157]
	ds_write_b128 v227, v[68:71] offset:1152
	ds_write_b128 v227, v[162:165] offset:2304
	ds_write_b128 v227, v[48:51] offset:3456
	s_waitcnt lgkmcnt(0)
	ds_read_b128 v[154:157], v225
	ds_read_b128 v[68:71], v225 offset:16
	ds_read_b128 v[162:165], v225 offset:32
	ds_read_b128 v[48:51], v225 offset:48
	s_waitcnt lgkmcnt(0)
	s_waitcnt lgkmcnt(0)
	v_mov_b32_e32 v176, v72
	s_waitcnt lgkmcnt(0)
	v_mov_b32_e32 v177, v76
	v_mov_b32_e32 v178, v116
	v_mov_b32_e32 v179, v154
	s_waitcnt lgkmcnt(0)
	v_add_f32_e32 v24, v24, v26
	v_fmamk_f32 v24, v24, 0x3c800000, v189
	v_rsq_f32_e32 v24, v24
	v_mov_b32_e32 v76, v73
	v_mov_b32_e32 v232, v74
	v_mov_b32_e32 v233, v78
	v_pk_mul_f32 v[180:181], v[24:25], v[238:239] op_sel_hi:[0,1]
	v_pk_mul_f32 v[176:177], v[176:177], v[180:181]
	v_mov_b32_e32 v174, v118
	v_pk_mul_f32 v[178:179], v[178:179], v[176:177]
	v_mov_b32_e32 v175, v156
	v_sub_f32_e32 v96, v178, v179
	v_mov_b32_e32 v178, v154
	v_mov_b32_e32 v179, v116
	v_pk_mul_f32 v[176:177], v[178:179], v[176:177]
	v_mov_b32_e32 v154, v117
	v_add_f32_e32 v153, v177, v176
	v_pk_mul_f32 v[176:177], v[24:25], v[244:245] op_sel_hi:[0,1]
	v_pk_mul_f32 v[72:73], v[76:77], v[176:177]
	v_mov_b32_e32 v116, v155
	v_pk_mul_f32 v[76:77], v[154:155], v[72:73]
	v_pk_mul_f32 v[72:73], v[116:117], v[72:73]
	v_sub_f32_e32 v154, v76, v77
	v_add_f32_e32 v116, v73, v72
	v_pk_mul_f32 v[72:73], v[24:25], v[228:229] op_sel_hi:[0,1]
	v_pk_mul_f32 v[72:73], v[232:233], v[72:73]
	v_mov_b32_e32 v78, v75
	v_pk_mul_f32 v[76:77], v[174:175], v[72:73]
	v_mov_b32_e32 v226, v44
	v_sub_f32_e32 v117, v76, v77
	v_mov_b32_e32 v76, v156
	v_mov_b32_e32 v77, v118
	v_pk_mul_f32 v[72:73], v[76:77], v[72:73]
	v_mov_b32_e32 v156, v119
	v_add_f32_e32 v76, v73, v72
	v_pk_mul_f32 v[72:73], v[24:25], v[234:235] op_sel_hi:[0,1]
	v_pk_mul_f32 v[72:73], v[78:79], v[72:73]
	v_mov_b32_e32 v118, v157
	v_pk_mul_f32 v[74:75], v[156:157], v[72:73]
	v_pk_mul_f32 v[72:73], v[118:119], v[72:73]
	v_mov_b32_e32 v227, v68
	v_add_f32_e32 v78, v73, v72
	v_pk_mul_f32 v[72:73], v[24:25], v[170:171] op_sel_hi:[0,1]
	v_pk_mul_f32 v[72:73], v[72:73], v[222:223]
	v_sub_f32_e32 v77, v74, v75
	v_pk_mul_f32 v[74:75], v[72:73], v[226:227]
	v_mov_b32_e32 v28, v25
	v_sub_f32_e32 v79, v74, v75
	v_mov_b32_e32 v74, v68
	v_mov_b32_e32 v75, v44
	v_pk_mul_f32 v[72:73], v[72:73], v[74:75]
	v_mov_b32_e32 v68, v45
	v_add_f32_e32 v74, v73, v72
	v_pk_mul_f32 v[72:73], v[24:25], v[172:173] op_sel_hi:[0,1]
	v_pk_mul_f32 v[28:29], v[72:73], v[28:29]
	v_mov_b32_e32 v44, v69
	v_pk_mul_f32 v[72:73], v[28:29], v[68:69]
	v_pk_mul_f32 v[28:29], v[28:29], v[44:45]
	v_sub_f32_e32 v25, v72, v73
	v_mov_b32_e32 v99, v30
	v_add_f32_e32 v68, v29, v28
	v_pk_mul_f32 v[28:29], v[24:25], v[166:167] op_sel_hi:[0,1]
	v_mov_b32_e32 v224, v46
	v_mov_b32_e32 v225, v70
	v_pk_mul_f32 v[28:29], v[28:29], v[98:99]
	v_mov_b32_e32 v30, v27
	v_pk_mul_f32 v[44:45], v[28:29], v[224:225]
	s_and_b64 vcc, exec, s[76:77]
	v_sub_f32_e32 v69, v44, v45
	v_mov_b32_e32 v44, v70
	v_mov_b32_e32 v45, v46
	v_pk_mul_f32 v[28:29], v[28:29], v[44:45]
	v_mov_b32_e32 v70, v47
	v_add_f32_e32 v44, v29, v28
	v_pk_mul_f32 v[28:29], v[24:25], v[168:169] op_sel_hi:[0,1]
	v_pk_mul_f32 v[26:27], v[28:29], v[30:31]
	v_mov_b32_e32 v46, v71
	v_pk_mul_f32 v[28:29], v[26:27], v[70:71]
	v_pk_mul_f32 v[26:27], v[26:27], v[46:47]
	v_sub_f32_e32 v30, v28, v29
	v_add_f32_e32 v31, v27, v26
	v_mov_b32_e32 v26, v65
	v_mov_b32_e32 v27, v67
	v_pk_mul_f32 v[26:27], v[24:25], v[26:27] op_sel_hi:[0,1]
	v_mov_b32_e32 v28, v32
	v_mov_b32_e32 v29, v36
	v_pk_mul_f32 v[26:27], v[26:27], v[28:29]
	v_mov_b32_e32 v28, v158
	v_mov_b32_e32 v29, v162
	v_pk_mul_f32 v[28:29], v[26:27], v[28:29]
	v_mov_b32_e32 v65, v66
	v_sub_f32_e32 v32, v28, v29
	v_mov_b32_e32 v28, v162
	v_mov_b32_e32 v29, v158
	v_pk_mul_f32 v[26:27], v[26:27], v[28:29]
	v_mov_b32_e32 v36, v33
	v_add_f32_e32 v45, v27, v26
	v_pk_mul_f32 v[26:27], v[24:25], v[64:65] op_sel_hi:[0,1]
	v_pk_mul_f32 v[26:27], v[26:27], v[36:37]
	v_mov_b32_e32 v162, v159
	v_mov_b32_e32 v158, v163
	v_pk_mul_f32 v[28:29], v[26:27], v[162:163]
	v_pk_mul_f32 v[26:27], v[26:27], v[158:159]
	v_sub_f32_e32 v33, v28, v29
	v_add_f32_e32 v36, v27, v26
	v_mov_b32_e32 v26, v61
	v_mov_b32_e32 v27, v63
	v_pk_mul_f32 v[26:27], v[24:25], v[26:27] op_sel_hi:[0,1]
	v_mov_b32_e32 v28, v34
	v_mov_b32_e32 v29, v38
	v_pk_mul_f32 v[26:27], v[26:27], v[28:29]
	v_mov_b32_e32 v28, v160
	v_mov_b32_e32 v29, v164
	v_pk_mul_f32 v[28:29], v[26:27], v[28:29]
	v_mov_b32_e32 v61, v62
	v_sub_f32_e32 v34, v28, v29
	v_mov_b32_e32 v28, v164
	v_mov_b32_e32 v29, v160
	v_pk_mul_f32 v[26:27], v[26:27], v[28:29]
	v_mov_b32_e32 v38, v35
	v_add_f32_e32 v37, v27, v26
	v_pk_mul_f32 v[26:27], v[24:25], v[60:61] op_sel_hi:[0,1]
	v_pk_mul_f32 v[26:27], v[26:27], v[38:39]
	v_mov_b32_e32 v164, v161
	v_mov_b32_e32 v160, v165
	v_pk_mul_f32 v[28:29], v[26:27], v[164:165]
	v_pk_mul_f32 v[26:27], v[26:27], v[160:161]
	v_sub_f32_e32 v35, v28, v29
	v_add_f32_e32 v38, v27, v26
	v_mov_b32_e32 v26, v57
	v_mov_b32_e32 v27, v59
	v_pk_mul_f32 v[26:27], v[24:25], v[26:27] op_sel_hi:[0,1]
	v_mov_b32_e32 v28, v16
	v_mov_b32_e32 v29, v20
	v_pk_mul_f32 v[26:27], v[26:27], v[28:29]
	v_mov_b32_e32 v28, v40
	v_mov_b32_e32 v29, v48
	v_pk_mul_f32 v[28:29], v[26:27], v[28:29]
	v_mov_b32_e32 v57, v58
	v_sub_f32_e32 v39, v28, v29
	v_mov_b32_e32 v28, v48
	v_mov_b32_e32 v29, v40
	v_pk_mul_f32 v[26:27], v[26:27], v[28:29]
	v_mov_b32_e32 v20, v17
	v_add_f32_e32 v28, v27, v26
	v_pk_mul_f32 v[26:27], v[24:25], v[56:57] op_sel_hi:[0,1]
	v_pk_mul_f32 v[16:17], v[26:27], v[20:21]
	v_mov_b32_e32 v48, v41
	v_mov_b32_e32 v40, v49
	v_pk_mul_f32 v[20:21], v[16:17], v[48:49]
	v_pk_mul_f32 v[16:17], v[16:17], v[40:41]
	v_sub_f32_e32 v26, v20, v21
	v_add_f32_e32 v27, v17, v16
	v_mov_b32_e32 v16, v53
	v_mov_b32_e32 v17, v55
	v_pk_mul_f32 v[16:17], v[24:25], v[16:17] op_sel_hi:[0,1]
	v_mov_b32_e32 v20, v18
	v_mov_b32_e32 v21, v22
	v_pk_mul_f32 v[16:17], v[16:17], v[20:21]
	v_mov_b32_e32 v20, v42
	v_mov_b32_e32 v21, v50
	v_pk_mul_f32 v[20:21], v[16:17], v[20:21]
	v_mov_b32_e32 v53, v54
	v_sub_f32_e32 v29, v20, v21
	v_mov_b32_e32 v20, v50
	v_mov_b32_e32 v21, v42
	v_pk_mul_f32 v[16:17], v[16:17], v[20:21]
	v_mov_b32_e32 v22, v19
	v_add_f32_e32 v20, v17, v16
	v_pk_mul_f32 v[16:17], v[24:25], v[52:53] op_sel_hi:[0,1]
	v_pk_mul_f32 v[16:17], v[16:17], v[22:23]
	v_mov_b32_e32 v50, v43
	v_mov_b32_e32 v42, v51
	v_pk_mul_f32 v[18:19], v[16:17], v[50:51]
	v_pk_mul_f32 v[16:17], v[16:17], v[42:43]
	v_sub_f32_e32 v21, v18, v19
	v_add_f32_e32 v22, v17, v16
	v_cvt_pk_bf16_f32 v16, v96, v154
	v_cvt_pk_bf16_f32 v17, v117, v77
	v_cvt_pk_bf16_f32 v18, v79, v25
	v_cvt_pk_bf16_f32 v19, v69, v30
	ds_write_b128 v190, v[16:19]
	v_cvt_pk_bf16_f32 v16, v32, v33
	v_cvt_pk_bf16_f32 v17, v34, v35
	v_cvt_pk_bf16_f32 v18, v39, v26
	v_cvt_pk_bf16_f32 v19, v29, v21
	ds_write_b128 v190, v[16:19] offset:16
	v_cvt_pk_bf16_f32 v16, v153, v116
	v_cvt_pk_bf16_f32 v17, v76, v78
	v_cvt_pk_bf16_f32 v18, v74, v68
	v_cvt_pk_bf16_f32 v19, v44, v31
	ds_write_b128 v190, v[16:19] offset:64
	v_cvt_pk_bf16_f32 v16, v45, v36
	v_cvt_pk_bf16_f32 v17, v37, v38
	v_cvt_pk_bf16_f32 v18, v28, v27
	v_cvt_pk_bf16_f32 v19, v20, v22
	ds_write_b128 v190, v[16:19] offset:80
	v_and_b32_e32 v16, 0xffff, v122
	v_lshrrev_b32_e32 v17, 16, v122
	v_lshl_or_b32 v16, v132, 16, v16
	v_and_or_b32 v17, v132, s54, v17
	v_add_u32_e32 v18, 0x9000, v191
	ds_write2_b32 v18, v16, v17 offset1:130
	v_and_b32_e32 v16, 0xffff, v123
	v_lshrrev_b32_e32 v17, 16, v123
	v_lshl_or_b32 v16, v133, 16, v16
	v_and_or_b32 v17, v133, s54, v17
	v_add_u32_e32 v18, 0x9400, v191
	ds_write2_b32 v18, v16, v17 offset0:4 offset1:134
	v_and_b32_e32 v16, 0xffff, v124
	v_lshrrev_b32_e32 v17, 16, v124
	v_lshl_or_b32 v16, v136, 16, v16
	v_and_or_b32 v17, v136, s54, v17
	v_add_u32_e32 v18, 0xb000, v191
	ds_write2_b32 v18, v16, v17 offset0:32 offset1:162
	v_and_b32_e32 v16, 0xffff, v125
	v_lshrrev_b32_e32 v17, 16, v125
	v_lshl_or_b32 v16, v137, 16, v16
	v_and_or_b32 v17, v137, s54, v17
	v_add_u32_e32 v18, 0xb400, v191
	ds_write2_b32 v18, v16, v17 offset0:36 offset1:166
	v_and_b32_e32 v16, 0xffff, v128
	v_lshrrev_b32_e32 v17, 16, v128
	v_lshl_or_b32 v16, v138, 16, v16
	v_and_or_b32 v17, v138, s54, v17
	v_add_u32_e32 v18, 0xd000, v191
	ds_write2_b32 v18, v16, v17 offset0:64 offset1:194
	v_and_b32_e32 v16, 0xffff, v129
	v_lshrrev_b32_e32 v17, 16, v129
	v_lshl_or_b32 v16, v139, 16, v16
	v_and_or_b32 v17, v139, s54, v17
	v_add_u32_e32 v18, 0xd400, v191
	ds_write2_b32 v18, v16, v17 offset0:68 offset1:198
	v_and_b32_e32 v16, 0xffff, v130
	v_lshrrev_b32_e32 v17, 16, v130
	v_lshl_or_b32 v16, v140, 16, v16
	v_and_or_b32 v17, v140, s54, v17
	v_add_u32_e32 v18, 0xf000, v191
	ds_write2_b32 v18, v16, v17 offset0:96 offset1:226
	v_and_b32_e32 v16, 0xffff, v131
	v_lshrrev_b32_e32 v17, 16, v131
	v_lshl_or_b32 v16, v141, 16, v16
	v_and_or_b32 v17, v141, s54, v17
	v_add_u32_e32 v18, 0xf400, v191
	ds_write2_b32 v18, v16, v17 offset0:100 offset1:230
	s_waitcnt vmcnt(0)
	v_and_b32_e32 v16, 63, v251
	v_lshrrev_b32_e32 v17, 3, v16
	v_mul_u32_u24_e32 v17, 0x90, v17
	v_and_b32_e32 v18, 7, v16
	v_lshl_add_u32 v17, v18, 4, v17
	v_mul_u32_u24_e32 v18, 0x1200, v254
	v_add_u32_e32 v18, 0x12000, v18
	v_add_u32_e32 v17, v17, v18
	v_and_b32_e32 v19, 31, v16
	v_mul_u32_u24_e32 v19, 0x90, v19
	v_lshrrev_b32_e32 v16, 5, v16
	v_lshl_add_u32 v19, v16, 4, v19
	v_add_u32_e32 v19, v19, v18
	ds_write_b128 v17, v[0:3]
	ds_write_b128 v17, v[4:7] offset:1152
	ds_write_b128 v17, v[8:11] offset:2304
	ds_write_b128 v17, v[12:15] offset:3456
	s_waitcnt lgkmcnt(0)
	ds_read_b128 v[0:3], v19
	ds_read_b128 v[8:11], v19 offset:32
	ds_read_b128 v[4:7], v19 offset:64
	ds_read_b128 v[12:15], v19 offset:96
	s_waitcnt lgkmcnt(0)
	ds_write_b128 v17, v[100:103]
	ds_write_b128 v17, v[104:107] offset:1152
	ds_write_b128 v17, v[108:111] offset:2304
	ds_write_b128 v17, v[112:115] offset:3456
	s_waitcnt lgkmcnt(0)
	ds_read_b128 v[100:103], v19
	ds_read_b128 v[108:111], v19 offset:32
	ds_read_b128 v[104:107], v19 offset:64
	ds_read_b128 v[112:115], v19 offset:96
	s_waitcnt lgkmcnt(0)
	s_barrier
	s_cbranch_vccnz .LBB0_354
	s_add_i32 s64, s1, s96
	s_and_b32 s64, s64, 0x780
	s_addk_i32 s64, 0xff80
	v_mov_b32_e32 v96, v97
	v_add_u32_e32 v16, s64, v182
	v_mov_b32_e32 v98, v97
	v_mov_b32_e32 v99, v97
	v_mov_b64_e32 v[80:81], v[96:97]
	v_mov_b64_e32 v[84:85], v[96:97]
	v_mov_b64_e32 v[92:93], v[96:97]
	v_mov_b64_e32 v[88:89], v[96:97]
	s_ashr_i32 s55, s33, 6
	s_and_b32 s69, s33, 3
	v_cmp_lt_i32_e32 vcc, -1, v16
	v_mov_b64_e32 v[82:83], v[98:99]
	v_mov_b64_e32 v[86:87], v[98:99]
	v_mov_b64_e32 v[94:95], v[98:99]
	v_mov_b64_e32 v[90:91], v[98:99]
	s_and_saveexec_b64 s[78:79], vcc
	s_cbranch_execz .LBB0_351
	v_readlane_b32 vcc_lo, v255, 6
	v_readlane_b32 vcc_hi, v255, 7
	v_add_u32_e32 v18, s64, v250
	v_lshl_add_u32 v18, s55, 11, v18
	s_lshl_b32 s94, s69, 7
	v_mov_b64_e32 v[16:17], vcc
	v_mad_i64_i32 v[16:17], vcc, v18, s65, v[16:17]
	v_lshl_add_u64 v[16:17], v[16:17], 0, s[94:95]
	v_mov_b32_e32 v153, v97
	v_lshl_add_u64 v[16:17], v[16:17], 0, v[248:249]
	s_movk_i32 s94, 0x6000
	global_load_dwordx4 v[80:83], v[16:17], off offset:2048
	v_lshl_add_u64 v[16:17], v[16:17], 0, s[94:95]
	global_load_dwordx4 v[84:87], v[16:17], off offset:2048
	v_lshl_add_u64 v[16:17], v[16:17], 0, s[94:95]
	global_load_dwordx4 v[88:91], v[16:17], off offset:2048
	v_lshl_add_u64 v[16:17], v[16:17], 0, s[94:95]
	global_load_dwordx4 v[92:95], v[16:17], off offset:2048

.LBB0_354:
	ds_read_b128 v[20:23], v243 offset:144
	ds_read_b128 v[16:19], v243 offset:16
	v_or_b32_e32 v153, s68, v184
	v_or_b32_e32 v98, s91, v153
	v_lshlrev_b32_e32 v96, 5, v98
	v_or_b32_e32 v24, v96, v126
	v_lshlrev_b32_e32 v54, 2, v24
	ds_read_b128 v[42:45], v243 offset:128
	ds_read_b128 v[24:27], v252 offset:4096
	ds_read_b128 v[28:31], v252 offset:22144
	ds_read_b128 v[46:49], v243
	ds_read_b128 v[50:53], v252
	s_nop 0
	ds_read_b128 v[54:57], v252 offset:16384
	s_lshl_b32 s55, s97, 2
	v_lshlrev_b32_e32 v34, 16, v15
	v_and_b32_e32 v32, 0xffff0000, v15
	v_lshlrev_b32_e32 v39, 16, v9
	v_and_b32_e32 v15, 0xffff0000, v9
	v_lshlrev_b32_e32 v41, 16, v8
	v_lshlrev_b32_e32 v40, 16, v12
	v_and_b32_e32 v9, 0xffff0000, v8
	v_and_b32_e32 v8, 0xffff0000, v12
	v_lshlrev_b32_e32 v12, 16, v7
	v_and_b32_e32 v58, 0xffff0000, v7
	v_lshlrev_b32_e32 v7, 16, v1
	v_and_b32_e32 v63, 0xffff0000, v1
	v_lshlrev_b32_e32 v65, 16, v0
	v_lshlrev_b32_e32 v64, 16, v4
	v_and_b32_e32 v1, 0xffff0000, v0
	v_and_b32_e32 v0, 0xffff0000, v4
	v_lshlrev_b32_e32 v35, 16, v11
	v_and_b32_e32 v33, 0xffff0000, v11
	v_lshlrev_b32_e32 v36, 16, v14
	v_lshlrev_b32_e32 v37, 16, v10
	v_and_b32_e32 v11, 0xffff0000, v10
	v_and_b32_e32 v10, 0xffff0000, v14
	v_lshlrev_b32_e32 v38, 16, v13
	v_and_b32_e32 v14, 0xffff0000, v13
	v_lshlrev_b32_e32 v13, 16, v3
	v_and_b32_e32 v59, 0xffff0000, v3
	v_lshlrev_b32_e32 v61, 16, v2
	v_lshlrev_b32_e32 v60, 16, v6
	v_and_b32_e32 v3, 0xffff0000, v2
	v_and_b32_e32 v2, 0xffff0000, v6
	v_lshlrev_b32_e32 v6, 16, v5
	v_mov_b32_e32 v99, s55
	v_pk_mul_f32 v[156:157], v[64:65], v[64:65]
	v_pk_mul_f32 v[158:159], v[0:1], v[0:1]
	v_and_b32_e32 v62, 0xffff0000, v5
	v_pk_mul_f32 v[118:119], v[6:7], v[6:7]
	v_mov_b32_e32 v214, v253
	v_add_f32_e32 v99, v157, v159
	v_pk_mul_f32 v[154:155], v[62:63], v[62:63]
	v_add_f32_e32 v99, v119, v99
	v_pk_mul_f32 v[78:79], v[60:61], v[60:61]
	v_add_f32_e32 v99, v155, v99
	v_pk_mul_f32 v[116:117], v[2:3], v[2:3]
	v_add_f32_e32 v79, v79, v99
	v_pk_mul_f32 v[74:75], v[12:13], v[12:13]
	v_add_f32_e32 v79, v117, v79
	v_pk_mul_f32 v[76:77], v[58:59], v[58:59]
	v_add_f32_e32 v75, v75, v79
	v_pk_mul_f32 v[70:71], v[40:41], v[40:41]
	v_add_f32_e32 v75, v77, v75
	v_pk_mul_f32 v[72:73], v[8:9], v[8:9]
	v_add_f32_e32 v71, v71, v75
	v_add_f32_e32 v71, v73, v71
	v_fmac_f32_e32 v71, v39, v39
	v_fmac_f32_e32 v71, v15, v15
	v_fmac_f32_e32 v71, v37, v37
	v_fmac_f32_e32 v71, v11, v11
	v_fmac_f32_e32 v71, v35, v35
	v_fmac_f32_e32 v71, v33, v33
	v_mov_b32_e32 v68, v14
	v_mov_b32_e32 v69, v38
	v_pk_mul_f32 v[68:69], v[68:69], v[68:69]
	v_mov_b32_e32 v66, v10
	v_mov_b32_e32 v67, v36
	v_pk_mul_f32 v[66:67], v[66:67], v[66:67]
	v_mov_b32_e32 v4, v32
	v_mov_b32_e32 v5, v34
	v_pk_mul_f32 v[4:5], v[4:5], v[4:5]
	s_waitcnt lgkmcnt(0)
	v_mov_b32_e32 v162, v20
	s_waitcnt lgkmcnt(0)
	v_mov_b32_e32 v163, v16
	v_add_f32_e32 v16, v156, v71
	v_add_f32_e32 v16, v158, v16
	v_add_f32_e32 v16, v118, v16
	v_add_f32_e32 v16, v154, v16
	v_add_f32_e32 v16, v78, v16
	v_add_f32_e32 v16, v116, v16
	v_add_f32_e32 v16, v74, v16
	v_add_f32_e32 v16, v76, v16
	v_add_f32_e32 v16, v70, v16
	v_add_f32_e32 v16, v72, v16
	v_add_f32_e32 v16, v69, v16
	v_add_f32_e32 v16, v68, v16
	v_add_f32_e32 v16, v67, v16
	v_add_f32_e32 v16, v66, v16
	v_add_f32_e32 v5, v5, v16
	v_add_f32_e32 v16, v4, v5
	v_mov_b32_e32 v161, v18
	ds_bpermute_b32 v18, v188, v16
	s_waitcnt lgkmcnt(0)
	v_mov_b32_e32 v66, v42
	s_waitcnt lgkmcnt(0)
	v_mov_b32_e32 v67, v46
	v_mov_b32_e32 v46, v43
	v_mov_b32_e32 v68, v50
	s_waitcnt lgkmcnt(0)
	v_add_f32_e32 v16, v16, v18
	v_fmamk_f32 v16, v16, 0x3c800000, v189
	v_rsq_f32_e32 v16, v16
	v_mov_b32_e32 v69, v54
	v_mov_b32_e32 v164, v44
	v_mov_b32_e32 v165, v48
	v_mul_f32_e32 v70, 0x3e38aa3b, v16
	v_pk_mul_f32 v[64:65], v[70:71], v[64:65] op_sel_hi:[0,1]
	v_pk_mul_f32 v[0:1], v[70:71], v[0:1] op_sel_hi:[0,1]
	v_pk_mul_f32 v[64:65], v[66:67], v[64:65]
	v_mov_b32_e32 v66, v54
	v_mov_b32_e32 v67, v50
	v_pk_mul_f32 v[0:1], v[46:47], v[0:1]
	v_mov_b32_e32 v50, v55
	v_mov_b32_e32 v54, v51
	v_pk_mul_f32 v[42:43], v[50:51], v[0:1]
	v_pk_mul_f32 v[0:1], v[54:55], v[0:1]
	v_sub_f32_e32 v42, v43, v42
	v_add_f32_e32 v43, v0, v1
	v_pk_mul_f32 v[0:1], v[70:71], v[6:7] op_sel_hi:[0,1]
	v_mov_b32_e32 v4, v52
	v_mov_b32_e32 v5, v56
	v_pk_mul_f32 v[0:1], v[0:1], v[164:165]
	v_mov_b32_e32 v6, v56
	v_mov_b32_e32 v7, v52
	v_pk_mul_f32 v[6:7], v[0:1], v[6:7]
	v_pk_mul_f32 v[0:1], v[0:1], v[4:5]
	v_sub_f32_e32 v6, v7, v6
	v_add_f32_e32 v7, v0, v1
	v_pk_mul_f32 v[0:1], v[70:71], v[62:63] op_sel_hi:[0,1]
	v_mov_b32_e32 v48, v45
	v_pk_mul_f32 v[0:1], v[0:1], v[48:49]
	v_mov_b32_e32 v52, v57
	v_mov_b32_e32 v56, v53
	v_pk_mul_f32 v[4:5], v[0:1], v[52:53]
	v_pk_mul_f32 v[0:1], v[0:1], v[56:57]
	v_mov_b32_e32 v168, v24
	v_add_f32_e32 v45, v0, v1
	v_pk_mul_f32 v[0:1], v[70:71], v[60:61] op_sel_hi:[0,1]
	v_mov_b32_e32 v169, v28
	v_sub_f32_e32 v44, v5, v4
	v_pk_mul_f32 v[0:1], v[0:1], v[162:163]
	v_mov_b32_e32 v4, v28
	v_mov_b32_e32 v5, v24
	v_pk_mul_f32 v[4:5], v[0:1], v[4:5]
	v_pk_mul_f32 v[0:1], v[0:1], v[168:169]
	v_sub_f32_e32 v4, v5, v4
	v_add_f32_e32 v5, v0, v1
	v_pk_mul_f32 v[0:1], v[70:71], v[2:3] op_sel_hi:[0,1]
	v_mov_b32_e32 v16, v21
	v_pk_mul_f32 v[0:1], v[0:1], v[16:17]
	v_mov_b32_e32 v24, v29
	v_mov_b32_e32 v28, v25
	v_pk_mul_f32 v[2:3], v[0:1], v[24:25]
	v_pk_mul_f32 v[0:1], v[0:1], v[28:29]
	v_mov_b32_e32 v160, v22
	v_add_f32_e32 v17, v0, v1
	v_pk_mul_f32 v[0:1], v[70:71], v[12:13] op_sel_hi:[0,1]
	v_mov_b32_e32 v166, v26
	v_mov_b32_e32 v167, v30
	v_sub_f32_e32 v16, v3, v2
	v_pk_mul_f32 v[0:1], v[0:1], v[160:161]
	v_mov_b32_e32 v2, v30
	v_mov_b32_e32 v3, v26
	v_pk_mul_f32 v[2:3], v[0:1], v[2:3]
	v_pk_mul_f32 v[0:1], v[0:1], v[166:167]
	v_mov_b32_e32 v18, v23
	v_add_f32_e32 v13, v0, v1
	v_pk_mul_f32 v[0:1], v[70:71], v[58:59] op_sel_hi:[0,1]
	v_pk_mul_f32 v[0:1], v[0:1], v[18:19]
	v_mov_b32_e32 v26, v31
	v_mov_b32_e32 v30, v27
	v_sub_f32_e32 v12, v3, v2
	v_pk_mul_f32 v[2:3], v[0:1], v[26:27]
	v_pk_mul_f32 v[0:1], v[0:1], v[30:31]
	v_pk_mul_f32 v[66:67], v[66:67], v[64:65]
	v_pk_mul_f32 v[64:65], v[68:69], v[64:65]
	v_sub_f32_e32 v2, v3, v2
	v_add_f32_e32 v0, v0, v1
	v_sub_f32_e32 v20, v67, v66
	v_add_f32_e32 v22, v64, v65
	v_cvt_pk_bf16_f32 v48, v20, v42
	v_cvt_pk_bf16_f32 v49, v6, v44
	v_cvt_pk_bf16_f32 v50, v4, v16
	v_cvt_pk_bf16_f32 v51, v12, v2
	v_cvt_pk_bf16_f32 v116, v22, v43
	v_cvt_pk_bf16_f32 v117, v7, v45
	v_cvt_pk_bf16_f32 v118, v5, v17
	v_cvt_pk_bf16_f32 v119, v13, v0
	ds_read_b128 v[0:3], v243 offset:192
	ds_read_b128 v[4:7], v243 offset:64
	v_or_b32_e32 v96, v96, v127
	v_lshlrev_b32_e32 v12, 2, v96
	ds_read_b128 v[16:19], v252 offset:26240
	ds_read_b128 v[20:23], v252 offset:8192
	ds_read_b128 v[24:27], v243 offset:208
	ds_read_b128 v[28:31], v243 offset:80
	ds_read_b128 v[42:45], v252 offset:30336
	ds_read_b128 v[52:55], v252 offset:12288
	v_pk_mul_f32 v[12:13], v[70:71], v[40:41] op_sel_hi:[0,1]
	v_pk_mul_f32 v[8:9], v[70:71], v[8:9] op_sel_hi:[0,1]
	s_lshl_b32 s69, s97, 6
	s_cmp_eq_u32 s88, 0
	s_cselect_b64 s[78:79], -1, 0
	s_cmp_lg_u32 s88, 0
	s_waitcnt lgkmcnt(0)
	v_mov_b32_e32 v40, v0
	s_waitcnt lgkmcnt(0)
	v_mov_b32_e32 v41, v4
	v_pk_mul_f32 v[12:13], v[12:13], v[40:41]
	v_mov_b32_e32 v40, v16
	v_mov_b32_e32 v41, v20
	v_pk_mul_f32 v[40:41], v[12:13], v[40:41]
	v_mov_b32_e32 v4, v1
	v_sub_f32_e32 v46, v41, v40
	v_mov_b32_e32 v40, v20
	v_mov_b32_e32 v41, v16
	v_pk_mul_f32 v[0:1], v[8:9], v[4:5]
	v_mov_b32_e32 v20, v17
	v_mov_b32_e32 v16, v21
	v_pk_mul_f32 v[4:5], v[0:1], v[20:21]
	v_pk_mul_f32 v[0:1], v[0:1], v[16:17]
	v_sub_f32_e32 v8, v5, v4
	v_add_f32_e32 v9, v0, v1
	v_pk_mul_f32 v[0:1], v[70:71], v[38:39] op_sel_hi:[0,1]
	v_mov_b32_e32 v4, v2
	v_mov_b32_e32 v5, v6
	v_pk_mul_f32 v[0:1], v[0:1], v[4:5]
	v_mov_b32_e32 v4, v18
	v_mov_b32_e32 v5, v22
	v_pk_mul_f32 v[12:13], v[12:13], v[40:41]
	v_pk_mul_f32 v[4:5], v[0:1], v[4:5]
	v_add_f32_e32 v12, v12, v13
	v_sub_f32_e32 v13, v5, v4
	v_mov_b32_e32 v4, v22
	v_mov_b32_e32 v5, v18
	v_pk_mul_f32 v[0:1], v[0:1], v[4:5]
	v_mov_b32_e32 v6, v3
	v_add_f32_e32 v4, v0, v1
	v_pk_mul_f32 v[0:1], v[70:71], v[14:15] op_sel_hi:[0,1]
	v_pk_mul_f32 v[0:1], v[0:1], v[6:7]
	v_mov_b32_e32 v22, v19
	v_mov_b32_e32 v18, v23
	v_pk_mul_f32 v[2:3], v[0:1], v[22:23]
	v_pk_mul_f32 v[0:1], v[0:1], v[18:19]
	v_sub_f32_e32 v5, v3, v2
	v_add_f32_e32 v6, v0, v1
	v_pk_mul_f32 v[0:1], v[70:71], v[36:37] op_sel_hi:[0,1]
	s_waitcnt lgkmcnt(0)
	v_mov_b32_e32 v2, v24
	s_waitcnt lgkmcnt(0)
	v_mov_b32_e32 v3, v28
	v_pk_mul_f32 v[0:1], v[0:1], v[2:3]
	v_mov_b32_e32 v2, v42
	v_mov_b32_e32 v3, v52
	v_pk_mul_f32 v[2:3], v[0:1], v[2:3]
	v_mov_b32_e32 v28, v25
	v_sub_f32_e32 v7, v3, v2
	v_mov_b32_e32 v2, v52
	v_mov_b32_e32 v3, v42
	v_pk_mul_f32 v[0:1], v[0:1], v[2:3]
	v_mov_b32_e32 v52, v43
	v_add_f32_e32 v14, v0, v1
	v_pk_mul_f32 v[0:1], v[70:71], v[10:11] op_sel_hi:[0,1]
	v_pk_mul_f32 v[0:1], v[0:1], v[28:29]
	v_mov_b32_e32 v42, v53
	v_pk_mul_f32 v[2:3], v[0:1], v[52:53]
	v_pk_mul_f32 v[0:1], v[0:1], v[42:43]
	v_sub_f32_e32 v10, v3, v2
	v_add_f32_e32 v11, v0, v1
	v_pk_mul_f32 v[0:1], v[70:71], v[34:35] op_sel_hi:[0,1]
	v_mov_b32_e32 v2, v26
	v_mov_b32_e32 v3, v30
	v_pk_mul_f32 v[0:1], v[0:1], v[2:3]
	v_mov_b32_e32 v2, v44
	v_mov_b32_e32 v3, v54
	v_pk_mul_f32 v[2:3], v[0:1], v[2:3]
	v_mov_b32_e32 v30, v27
	v_sub_f32_e32 v15, v3, v2
	v_mov_b32_e32 v2, v54
	v_mov_b32_e32 v3, v44
	v_pk_mul_f32 v[0:1], v[0:1], v[2:3]
	v_mov_b32_e32 v54, v45
	v_add_f32_e32 v16, v0, v1
	v_pk_mul_f32 v[0:1], v[70:71], v[32:33] op_sel_hi:[0,1]
	v_pk_mul_f32 v[0:1], v[0:1], v[30:31]
	v_mov_b32_e32 v44, v55
	v_pk_mul_f32 v[2:3], v[0:1], v[54:55]
	v_pk_mul_f32 v[0:1], v[0:1], v[44:45]
	v_sub_f32_e32 v2, v3, v2
	v_add_f32_e32 v0, v0, v1
	v_cvt_pk_bf16_f32 v154, v46, v8
	v_cvt_pk_bf16_f32 v155, v13, v5
	v_cvt_pk_bf16_f32 v156, v7, v10
	v_cvt_pk_bf16_f32 v157, v15, v2
	v_cvt_pk_bf16_f32 v158, v12, v9
	v_cvt_pk_bf16_f32 v159, v4, v6
	v_cvt_pk_bf16_f32 v160, v14, v11
	v_cvt_pk_bf16_f32 v161, v16, v0
	ds_read_b128 v[0:3], v192
	ds_read_b128 v[52:55], v195 offset:32
	s_waitcnt lgkmcnt(1)
	v_mfma_f32_32x32x16_bf16 v[64:79], v[0:3], v[48:51], 0
	ds_read_b128 v[0:3], v192 offset:32
	ds_read_b128 v[162:165], v196 offset:32
	s_waitcnt lgkmcnt(1)
	v_mfma_f32_32x32x16_bf16 v[64:79], v[0:3], v[154:157], v[64:79]
	ds_read_b128 v[0:3], v192 offset:64
	s_waitcnt lgkmcnt(0)
	v_mfma_f32_32x32x16_bf16 v[64:79], v[0:3], v[116:119], v[64:79]
	ds_read_b128 v[0:3], v192 offset:96
	s_waitcnt lgkmcnt(0)
	v_mfma_f32_32x32x16_bf16 v[64:79], v[0:3], v[158:161], v[64:79]
	ds_read_b128 v[0:3], v193
	s_waitcnt lgkmcnt(0)
	v_mfma_f32_32x32x16_bf16 v[32:47], v[0:3], v[48:51], 0
	ds_read_b128 v[0:3], v193 offset:32
	s_waitcnt lgkmcnt(0)
	v_mfma_f32_32x32x16_bf16 v[32:47], v[0:3], v[154:157], v[32:47]
	ds_read_b128 v[0:3], v193 offset:64
	s_waitcnt lgkmcnt(0)
	v_mfma_f32_32x32x16_bf16 v[32:47], v[0:3], v[116:119], v[32:47]
	ds_read_b128 v[0:3], v193 offset:96
	s_waitcnt lgkmcnt(0)
	v_mfma_f32_32x32x16_bf16 v[32:47], v[0:3], v[158:161], v[32:47]
	ds_read_b128 v[0:3], v194
	s_waitcnt lgkmcnt(0)
	v_mfma_f32_32x32x16_bf16 v[16:31], v[0:3], v[48:51], 0
	ds_read_b128 v[0:3], v194 offset:32
	s_waitcnt lgkmcnt(0)
	v_mfma_f32_32x32x16_bf16 v[16:31], v[0:3], v[154:157], v[16:31]
	ds_read_b128 v[0:3], v194 offset:64
	s_waitcnt lgkmcnt(0)
	v_mfma_f32_32x32x16_bf16 v[16:31], v[0:3], v[116:119], v[16:31]
	ds_read_b128 v[0:3], v194 offset:96
	s_waitcnt lgkmcnt(0)
	v_mfma_f32_32x32x16_bf16 v[16:31], v[0:3], v[158:161], v[16:31]
	ds_read_b128 v[0:3], v195
	s_waitcnt lgkmcnt(0)
	v_mfma_f32_32x32x16_bf16 v[0:15], v[0:3], v[48:51], 0
	v_mfma_f32_32x32x16_bf16 v[0:15], v[52:55], v[154:157], v[0:15]
	ds_read_b128 v[52:55], v195 offset:64
	s_waitcnt lgkmcnt(0)
	v_mfma_f32_32x32x16_bf16 v[0:15], v[52:55], v[116:119], v[0:15]
	ds_read_b128 v[52:55], v195 offset:96
	s_waitcnt lgkmcnt(0)
	v_mfma_f32_32x32x16_bf16 v[0:15], v[52:55], v[158:161], v[0:15]
	ds_read_b128 v[52:55], v196
	s_waitcnt lgkmcnt(0)
	v_mfma_f32_32x32x16_bf16 v[48:63], v[52:55], v[48:51], 0
	v_mfma_f32_32x32x16_bf16 v[48:63], v[162:165], v[154:157], v[48:63]
	ds_read_b128 v[154:157], v196 offset:64
	s_waitcnt lgkmcnt(0)
	v_mfma_f32_32x32x16_bf16 v[48:63], v[154:157], v[116:119], v[48:63]
	ds_read_b128 v[116:119], v196 offset:96
	s_waitcnt lgkmcnt(0)
	v_mfma_f32_32x32x16_bf16 v[48:63], v[116:119], v[158:161], v[48:63]
	s_cbranch_scc0 .LBB0_356
	v_cndmask_b32_e64 v158, v212, v64, s[2:3]
	v_cndmask_b32_e64 v157, v65, v212, s[4:5]
	v_cndmask_b32_e64 v156, v212, v66, s[6:7]
	v_cndmask_b32_e64 v155, v212, v67, s[8:9]
	v_cndmask_b32_e64 v154, v212, v68, s[10:11]
	v_cndmask_b32_e64 v119, v212, v69, s[12:13]
	v_cndmask_b32_e64 v118, v212, v70, s[14:15]
	v_cndmask_b32_e64 v99, v212, v71, s[16:17]
	v_cndmask_b32_e64 v71, v212, v72, s[18:19]
	v_cndmask_b32_e64 v70, v212, v73, s[20:21]
	v_cndmask_b32_e64 v69, v212, v74, s[22:23]
	v_cndmask_b32_e64 v68, v212, v75, s[24:25]
	v_cndmask_b32_e64 v67, v212, v76, s[26:27]
	v_cndmask_b32_e64 v66, v212, v77, s[28:29]
	v_cndmask_b32_e64 v65, v212, v78, s[30:31]
	v_cndmask_b32_e64 v64, v212, v79, s[34:35]
	s_branch .LBB0_357

.LBB0_357:
	s_mov_b32 s64, 0xff800000
	v_cndmask_b32_e64 v72, v48, v212, s[2:3]
	v_cndmask_b32_e64 v216, v72, v48, s[4:5]
	v_max3_f32 v48, v158, s64, v157
	v_max3_f32 v48, v48, v156, v155
	v_max3_f32 v48, v48, v154, v119
	v_max3_f32 v48, v48, v118, v99
	v_max3_f32 v48, v48, v71, v70
	v_max3_f32 v48, v48, v69, v68
	v_max3_f32 v48, v48, v67, v66
	v_max3_f32 v48, v48, v65, v64
	v_max3_f32 v48, v48, v32, v33
	v_max3_f32 v48, v48, v34, v35
	v_max3_f32 v48, v48, v36, v37
	v_max3_f32 v48, v48, v38, v39
	v_max3_f32 v48, v48, v40, v41
	v_max3_f32 v48, v48, v42, v43
	v_max3_f32 v48, v48, v44, v45
	v_max3_f32 v48, v48, v46, v47
	v_max3_f32 v48, v48, v16, v17
	v_max3_f32 v48, v48, v18, v19
	v_max3_f32 v48, v48, v20, v21
	v_max3_f32 v48, v48, v22, v23
	v_max3_f32 v48, v48, v24, v25
	v_max3_f32 v48, v48, v26, v27
	v_max3_f32 v48, v48, v28, v29
	v_max3_f32 v48, v48, v30, v31
	v_max3_f32 v48, v48, v0, v1
	v_max3_f32 v48, v48, v2, v3
	v_max3_f32 v48, v48, v4, v5
	v_max3_f32 v48, v48, v6, v7
	v_max3_f32 v48, v48, v8, v9
	v_max3_f32 v48, v48, v10, v11
	v_max3_f32 v48, v48, v12, v13
	v_cndmask_b32_e64 v215, v212, v49, s[4:5]
	v_max3_f32 v48, v48, v14, v15
	v_cndmask_b32_e64 v217, v50, v212, s[6:7]
	v_cndmask_b32_e64 v218, v51, v212, s[8:9]
	v_max3_f32 v48, v48, v216, v215
	v_cndmask_b32_e64 v219, v52, v212, s[10:11]
	v_cndmask_b32_e64 v220, v53, v212, s[12:13]
	v_max3_f32 v48, v48, v217, v218
	v_cndmask_b32_e64 v221, v54, v212, s[14:15]
	v_cndmask_b32_e64 v222, v55, v212, s[16:17]
	v_max3_f32 v48, v48, v219, v220
	v_cndmask_b32_e64 v223, v56, v212, s[18:19]
	v_cndmask_b32_e64 v224, v57, v212, s[20:21]
	v_max3_f32 v48, v48, v221, v222
	v_cndmask_b32_e64 v225, v58, v212, s[22:23]
	v_cndmask_b32_e64 v226, v59, v212, s[24:25]
	v_max3_f32 v48, v48, v223, v224
	v_cndmask_b32_e64 v227, v60, v212, s[26:27]
	v_cndmask_b32_e64 v228, v61, v212, s[28:29]
	v_max3_f32 v48, v48, v225, v226
	v_cndmask_b32_e64 v229, v62, v212, s[30:31]
	v_cndmask_b32_e64 v230, v63, v212, s[34:35]
	v_max3_f32 v48, v48, v227, v228
	v_max3_f32 v48, v48, v229, v230
	ds_bpermute_b32 v49, v188, v48
	v_mul_f32_e32 v96, 0x3fb8aa3b, v214
	v_or_b32_e32 v213, s89, v98
	s_mov_b32 s55, 0x3fb8aa3b
	s_lshl_b32 s94, s69, 1
	s_waitcnt lgkmcnt(0)
	v_max3_f32 v231, v48, v49, v96
	v_sub_f32_e32 v50, v156, v231
	v_exp_f32_e32 v170, v50
	v_sub_f32_e32 v50, v155, v231
	v_exp_f32_e32 v171, v50
	v_sub_f32_e32 v50, v154, v231
	v_exp_f32_e32 v176, v50
	v_sub_f32_e32 v50, v119, v231
	v_exp_f32_e32 v177, v50
	v_sub_f32_e32 v50, v118, v231
	v_sub_f32_e32 v48, v158, v231
	v_exp_f32_e32 v180, v50
	v_sub_f32_e32 v50, v99, v231
	v_exp_f32_e32 v162, v48
	v_sub_f32_e32 v48, v157, v231
	v_exp_f32_e32 v181, v50
	v_sub_f32_e32 v50, v71, v231
	v_exp_f32_e32 v163, v48
	v_exp_f32_e32 v154, v50
	v_sub_f32_e32 v50, v70, v231
	v_exp_f32_e32 v155, v50
	v_sub_f32_e32 v50, v69, v231
	v_sub_f32_e32 v34, v34, v231
	v_exp_f32_e32 v164, v50
	v_sub_f32_e32 v50, v68, v231
	v_exp_f32_e32 v158, v34
	v_sub_f32_e32 v34, v35, v231
	v_exp_f32_e32 v165, v50
	v_sub_f32_e32 v50, v67, v231
	v_exp_f32_e32 v159, v34
	v_sub_f32_e32 v34, v36, v231
	v_pk_add_f32 v[48:49], v[162:163], 0 op_sel_hi:[1,0]
	v_exp_f32_e32 v172, v50
	v_sub_f32_e32 v50, v66, v231
	v_exp_f32_e32 v166, v34
	v_sub_f32_e32 v34, v37, v231
	v_pk_add_f32 v[48:49], v[170:171], v[48:49]
	v_exp_f32_e32 v173, v50
	v_sub_f32_e32 v50, v65, v231
	v_exp_f32_e32 v167, v34
	v_sub_f32_e32 v34, v38, v231
	v_pk_add_f32 v[48:49], v[176:177], v[48:49]
	v_exp_f32_e32 v178, v50
	v_sub_f32_e32 v50, v64, v231
	v_sub_f32_e32 v32, v32, v231
	v_exp_f32_e32 v174, v34
	v_sub_f32_e32 v34, v39, v231
	v_pk_add_f32 v[48:49], v[180:181], v[48:49]
	v_exp_f32_e32 v179, v50
	v_exp_f32_e32 v78, v32
	v_sub_f32_e32 v32, v33, v231
	v_exp_f32_e32 v175, v34
	v_sub_f32_e32 v34, v40, v231
	v_pk_add_f32 v[48:49], v[154:155], v[48:49]
	v_exp_f32_e32 v79, v32
	v_exp_f32_e32 v70, v34
	v_sub_f32_e32 v34, v41, v231
	v_pk_add_f32 v[48:49], v[164:165], v[48:49]
	v_exp_f32_e32 v71, v34
	v_sub_f32_e32 v34, v42, v231
	v_sub_f32_e32 v18, v18, v231
	v_sub_f32_e32 v2, v2, v231
	v_pk_add_f32 v[48:49], v[172:173], v[48:49]
	v_exp_f32_e32 v76, v34
	v_sub_f32_e32 v34, v43, v231
	v_exp_f32_e32 v74, v18
	v_sub_f32_e32 v18, v19, v231
	v_exp_f32_e32 v60, v2
	v_sub_f32_e32 v2, v3, v231
	v_pk_add_f32 v[48:49], v[178:179], v[48:49]
	v_exp_f32_e32 v77, v34
	v_sub_f32_e32 v34, v44, v231
	v_exp_f32_e32 v75, v18
	v_sub_f32_e32 v18, v20, v231
	v_exp_f32_e32 v61, v2
	v_sub_f32_e32 v2, v4, v231
	v_pk_add_f32 v[32:33], v[78:79], v[48:49]
	v_exp_f32_e32 v156, v34
	v_sub_f32_e32 v34, v45, v231
	v_exp_f32_e32 v98, v18
	v_sub_f32_e32 v18, v21, v231
	v_exp_f32_e32 v66, v2
	v_sub_f32_e32 v2, v5, v231
	v_pk_add_f32 v[32:33], v[158:159], v[32:33]
	v_exp_f32_e32 v157, v34
	v_sub_f32_e32 v34, v46, v231
	v_exp_f32_e32 v99, v18
	v_sub_f32_e32 v18, v22, v231
	v_exp_f32_e32 v67, v2
	v_sub_f32_e32 v2, v6, v231
	v_pk_add_f32 v[32:33], v[166:167], v[32:33]
	v_exp_f32_e32 v168, v34
	v_sub_f32_e32 v34, v47, v231
	v_sub_f32_e32 v16, v16, v231
	v_exp_f32_e32 v160, v18
	v_sub_f32_e32 v18, v23, v231
	v_exp_f32_e32 v68, v2
	v_sub_f32_e32 v2, v7, v231
	v_pk_add_f32 v[32:33], v[174:175], v[32:33]
	v_exp_f32_e32 v169, v34
	v_exp_f32_e32 v64, v16
	v_sub_f32_e32 v16, v17, v231
	v_exp_f32_e32 v161, v18
	v_sub_f32_e32 v18, v24, v231
	v_exp_f32_e32 v69, v2
	v_sub_f32_e32 v2, v8, v231
	v_pk_add_f32 v[32:33], v[70:71], v[32:33]
	v_exp_f32_e32 v65, v16
	v_exp_f32_e32 v58, v18
	v_sub_f32_e32 v18, v25, v231
	v_exp_f32_e32 v48, v2
	v_sub_f32_e32 v2, v9, v231
	v_pk_add_f32 v[32:33], v[76:77], v[32:33]
	v_exp_f32_e32 v59, v18
	v_sub_f32_e32 v18, v26, v231
	v_exp_f32_e32 v49, v2
	v_sub_f32_e32 v2, v10, v231
	v_pk_add_f32 v[32:33], v[156:157], v[32:33]
	v_exp_f32_e32 v62, v18
	v_sub_f32_e32 v18, v27, v231
	v_exp_f32_e32 v50, v2
	v_sub_f32_e32 v2, v11, v231
	v_pk_add_f32 v[32:33], v[168:169], v[32:33]
	v_exp_f32_e32 v63, v18
	v_sub_f32_e32 v18, v28, v231
	v_exp_f32_e32 v51, v2
	v_sub_f32_e32 v2, v12, v231
	v_pk_add_f32 v[16:17], v[64:65], v[32:33]
	v_exp_f32_e32 v72, v18
	v_sub_f32_e32 v18, v29, v231
	v_exp_f32_e32 v52, v2
	v_sub_f32_e32 v2, v13, v231
	v_pk_add_f32 v[16:17], v[74:75], v[16:17]
	v_exp_f32_e32 v73, v18
	v_sub_f32_e32 v18, v30, v231
	v_exp_f32_e32 v53, v2
	v_sub_f32_e32 v2, v14, v231
	v_pk_add_f32 v[16:17], v[98:99], v[16:17]
	v_exp_f32_e32 v118, v18
	v_sub_f32_e32 v18, v31, v231
	v_sub_f32_e32 v0, v0, v231
	v_exp_f32_e32 v54, v2
	v_sub_f32_e32 v2, v15, v231
	v_pk_add_f32 v[16:17], v[160:161], v[16:17]
	v_exp_f32_e32 v119, v18
	v_exp_f32_e32 v56, v0
	v_sub_f32_e32 v0, v1, v231
	v_exp_f32_e32 v55, v2
	v_sub_f32_e32 v2, v216, v231
	v_pk_add_f32 v[16:17], v[58:59], v[16:17]
	v_exp_f32_e32 v57, v0
	v_exp_f32_e32 v40, v2
	v_sub_f32_e32 v2, v215, v231
	v_pk_add_f32 v[16:17], v[62:63], v[16:17]
	v_exp_f32_e32 v41, v2
	v_sub_f32_e32 v2, v217, v231
	v_pk_add_f32 v[16:17], v[72:73], v[16:17]
	v_exp_f32_e32 v42, v2
	v_sub_f32_e32 v2, v218, v231
	v_pk_add_f32 v[16:17], v[118:119], v[16:17]
	v_exp_f32_e32 v43, v2
	v_sub_f32_e32 v2, v219, v231
	v_pk_add_f32 v[0:1], v[56:57], v[16:17]
	v_exp_f32_e32 v44, v2
	v_sub_f32_e32 v2, v220, v231
	v_pk_add_f32 v[0:1], v[60:61], v[0:1]
	v_exp_f32_e32 v45, v2
	v_sub_f32_e32 v2, v221, v231
	v_pk_add_f32 v[0:1], v[66:67], v[0:1]
	v_exp_f32_e32 v46, v2
	v_sub_f32_e32 v2, v222, v231
	v_pk_add_f32 v[0:1], v[68:69], v[0:1]
	v_exp_f32_e32 v47, v2
	v_sub_f32_e32 v2, v223, v231
	v_pk_add_f32 v[0:1], v[48:49], v[0:1]
	v_exp_f32_e32 v32, v2
	v_sub_f32_e32 v2, v224, v231
	v_pk_add_f32 v[0:1], v[50:51], v[0:1]
	v_exp_f32_e32 v33, v2
	v_sub_f32_e32 v2, v225, v231
	v_pk_add_f32 v[0:1], v[52:53], v[0:1]
	v_exp_f32_e32 v34, v2
	v_sub_f32_e32 v2, v226, v231
	v_pk_add_f32 v[0:1], v[54:55], v[0:1]
	v_exp_f32_e32 v35, v2
	v_sub_f32_e32 v2, v227, v231
	v_pk_add_f32 v[0:1], v[40:41], v[0:1]
	v_exp_f32_e32 v36, v2
	v_sub_f32_e32 v2, v228, v231
	v_pk_add_f32 v[0:1], v[42:43], v[0:1]
	v_exp_f32_e32 v37, v2
	v_sub_f32_e32 v2, v229, v231
	v_pk_add_f32 v[0:1], v[44:45], v[0:1]
	v_exp_f32_e32 v38, v2
	v_sub_f32_e32 v2, v230, v231
	v_pk_add_f32 v[0:1], v[46:47], v[0:1]
	v_exp_f32_e32 v39, v2
	v_pk_add_f32 v[0:1], v[32:33], v[0:1]
	v_cvt_pk_bf16_f32 v16, v162, v163
	v_cvt_pk_bf16_f32 v17, v170, v171
	v_add_u32_e32 v170, 0x9000, v197
	v_pk_add_f32 v[0:1], v[34:35], v[0:1]
	v_cvt_pk_bf16_f32 v18, v176, v177
	v_cvt_pk_bf16_f32 v19, v180, v181
	v_add_u32_e32 v176, 0xd000, v197
	v_pk_add_f32 v[0:1], v[36:37], v[0:1]
	ds_read2_b64 v[20:23], v176 offset0:32 offset1:34
	v_pk_add_f32 v[0:1], v[38:39], v[0:1]
	v_lshl_add_u64 v[116:117], v[146:147], 0, s[94:95]
	v_add_f32_e32 v0, v0, v1
	ds_bpermute_b32 v1, v188, v0
	s_mov_b32 s97, s0
	v_readlane_b32 s0, v255, 15
	s_waitcnt lgkmcnt(0)
	v_add_f32_e32 v0, v0, v1
	v_fma_f32 v1, v214, s55, -v231
	v_exp_f32_e32 v1, v1
	s_nop 0
	v_add_f32_e32 v214, v1, v0
	ds_read2_b64 v[0:3], v170 offset1:2
	v_cvt_pk_bf16_f32 v162, v154, v155
	v_cvt_pk_bf16_f32 v163, v164, v165
	v_cvt_pk_bf16_f32 v164, v172, v173
	v_cvt_pk_bf16_f32 v165, v178, v179
	ds_read2_b64 v[170:173], v170 offset0:4 offset1:6
	s_waitcnt lgkmcnt(1)
	v_mfma_f32_32x32x16_bf16 v[0:15], v[0:3], v[16:19], 0
	s_waitcnt lgkmcnt(0)
	v_mfma_f32_32x32x16_bf16 v[0:15], v[170:173], v[162:165], v[0:15]
	ds_read2_b64 v[170:173], v176 offset0:36 offset1:38
	v_mfma_f32_32x32x16_bf16 v[16:31], v[20:23], v[16:19], 0
	s_waitcnt lgkmcnt(0)
	v_mfma_f32_32x32x16_bf16 v[16:31], v[170:173], v[162:165], v[16:31]
	v_cvt_pk_bf16_f32 v162, v78, v79
	v_add_u32_e32 v78, 0x9000, v198
	v_cvt_pk_bf16_f32 v163, v158, v159
	v_cvt_pk_bf16_f32 v164, v166, v167
	v_cvt_pk_bf16_f32 v165, v174, v175
	ds_read2_b64 v[170:173], v78 offset1:2
	v_add_u32_e32 v158, 0xd000, v198
	s_waitcnt lgkmcnt(0)
	v_mfma_f32_32x32x16_bf16 v[0:15], v[170:173], v[162:165], v[0:15]
	ds_read2_b64 v[170:173], v158 offset0:32 offset1:34
	v_cvt_pk_bf16_f32 v154, v70, v71
	v_cvt_pk_bf16_f32 v155, v76, v77
	v_cvt_pk_bf16_f32 v156, v156, v157
	v_cvt_pk_bf16_f32 v157, v168, v169
	ds_read2_b64 v[76:79], v78 offset0:4 offset1:6
	s_waitcnt lgkmcnt(0)
	v_mfma_f32_32x32x16_bf16 v[0:15], v[76:79], v[154:157], v[0:15]
	ds_read2_b64 v[76:79], v158 offset0:36 offset1:38
	v_mfma_f32_32x32x16_bf16 v[16:31], v[170:173], v[162:165], v[16:31]
	s_waitcnt lgkmcnt(0)
	v_mfma_f32_32x32x16_bf16 v[16:31], v[76:79], v[154:157], v[16:31]
	v_cvt_pk_bf16_f32 v76, v64, v65
	v_add_u32_e32 v64, 0x9000, v199
	v_cvt_pk_bf16_f32 v77, v74, v75
	v_cvt_pk_bf16_f32 v78, v98, v99
	v_cvt_pk_bf16_f32 v79, v160, v161
	ds_read2_b64 v[154:157], v64 offset1:2
	v_add_u32_e32 v74, 0xd000, v199
	s_waitcnt lgkmcnt(0)
	v_mfma_f32_32x32x16_bf16 v[0:15], v[154:157], v[76:79], v[0:15]
	ds_read2_b64 v[154:157], v74 offset0:32 offset1:34
	v_cvt_pk_bf16_f32 v70, v58, v59
	v_cvt_pk_bf16_f32 v71, v62, v63
	v_cvt_pk_bf16_f32 v72, v72, v73
	v_cvt_pk_bf16_f32 v73, v118, v119
	ds_read2_b64 v[62:65], v64 offset0:4 offset1:6
	v_or_b32_e32 v118, s0, v153
	s_waitcnt lgkmcnt(0)
	v_mfma_f32_32x32x16_bf16 v[0:15], v[62:65], v[70:73], v[0:15]
	ds_read2_b64 v[62:65], v74 offset0:36 offset1:38
	v_cvt_pk_bf16_f32 v56, v56, v57
	v_cvt_pk_bf16_f32 v57, v60, v61
	v_cvt_pk_bf16_f32 v58, v66, v67
	v_cvt_pk_bf16_f32 v59, v68, v69
	v_and_b32_e32 v67, 0xffff0000, v103
	v_and_b32_e32 v66, 0xffff0000, v107
	v_mfma_f32_32x32x16_bf16 v[16:31], v[154:157], v[76:79], v[16:31]
	v_lshlrev_b32_e32 v155, 16, v100
	v_lshlrev_b32_e32 v154, 16, v104
	v_and_b32_e32 v79, 0xffff0000, v102
	v_mul_f32_e64 v156, v154, v154
	v_mul_f32_e64 v157, v155, v155
	v_and_b32_e32 v78, 0xffff0000, v106
	v_pk_mul_f32 v[98:99], v[78:79], v[78:79]
	v_pk_mul_f32 v[68:69], v[66:67], v[66:67]
	s_waitcnt lgkmcnt(0)
	v_mfma_f32_32x32x16_bf16 v[16:31], v[62:65], v[70:73], v[16:31]
	v_add_u32_e32 v64, 0x9000, v200
	ds_read2_b64 v[60:63], v64 offset1:2
	v_add_u32_e32 v65, 0xd000, v200
	v_lshlrev_b32_e32 v71, 16, v102
	v_lshlrev_b32_e32 v102, 16, v105
	v_lshlrev_b32_e32 v70, 16, v106
	v_pk_mul_f32 v[72:73], v[70:71], v[70:71]
	s_waitcnt lgkmcnt(0)
	v_mfma_f32_32x32x16_bf16 v[0:15], v[60:63], v[56:59], v[0:15]
	ds_read2_b64 v[60:63], v65 offset0:32 offset1:34
	v_cvt_pk_bf16_f32 v48, v48, v49
	v_cvt_pk_bf16_f32 v49, v50, v51
	v_cvt_pk_bf16_f32 v50, v52, v53
	v_cvt_pk_bf16_f32 v51, v54, v55
	ds_read2_b64 v[52:55], v64 offset0:4 offset1:6
	s_waitcnt lgkmcnt(0)
	v_mfma_f32_32x32x16_bf16 v[0:15], v[52:55], v[48:51], v[0:15]
	ds_read2_b64 v[52:55], v65 offset0:36 offset1:38
	v_cvt_pk_bf16_f32 v40, v40, v41
	v_cvt_pk_bf16_f32 v41, v42, v43
	v_cvt_pk_bf16_f32 v42, v44, v45
	v_cvt_pk_bf16_f32 v43, v46, v47
	v_mfma_f32_32x32x16_bf16 v[16:31], v[60:63], v[56:59], v[16:31]
	v_lshlrev_b32_e32 v59, 16, v103
	v_lshlrev_b32_e32 v103, 16, v101
	v_lshlrev_b32_e32 v58, 16, v107
	v_mul_f32_e64 v106, v102, v102
	v_mul_f32_e64 v107, v103, v103
	v_pk_mul_f32 v[60:61], v[58:59], v[58:59]
	s_waitcnt lgkmcnt(0)
	v_mfma_f32_32x32x16_bf16 v[16:31], v[52:55], v[48:51], v[16:31]
	v_add_u32_e32 v48, 0x9000, v201
	ds_read2_b64 v[44:47], v48 offset1:2
	v_add_u32_e32 v49, 0xd000, v201
	s_waitcnt lgkmcnt(0)
	v_mfma_f32_32x32x16_bf16 v[0:15], v[44:47], v[40:43], v[0:15]
	ds_read2_b64 v[44:47], v49 offset0:32 offset1:34
	v_cvt_pk_bf16_f32 v32, v32, v33
	v_cvt_pk_bf16_f32 v33, v34, v35
	v_cvt_pk_bf16_f32 v34, v36, v37
	v_cvt_pk_bf16_f32 v35, v38, v39
	ds_read2_b64 v[36:39], v48 offset0:4 offset1:6
	s_waitcnt lgkmcnt(0)
	v_mfma_f32_32x32x16_bf16 v[0:15], v[36:39], v[32:35], v[0:15]
	ds_read2_b64 v[36:39], v49 offset0:36 offset1:38
	v_mfma_f32_32x32x16_bf16 v[16:31], v[44:47], v[40:43], v[16:31]
	v_lshlrev_b32_e32 v42, 16, v112
	v_lshlrev_b32_e32 v43, 16, v108
	v_mul_f32_e64 v54, v42, v42
	v_mul_f32_e64 v55, v43, v43
	s_waitcnt lgkmcnt(0)
	v_mfma_f32_32x32x16_bf16 v[16:31], v[36:39], v[32:35], v[16:31]
	v_div_scale_f32 v32, s[68:69], v214, v214, 1.0
	v_rcp_f32_e32 v33, v32
	v_lshlrev_b32_e32 v38, 16, v113
	v_mov_b32_e32 v41, v38
	v_lshlrev_b32_e32 v39, 16, v109
	v_fma_f32 v34, -v32, v33, 1.0
	v_fmac_f32_e32 v33, v34, v33
	v_div_scale_f32 v34, vcc, 1.0, v214, 1.0
	v_mul_f32_e32 v35, v34, v33
	v_fma_f32 v36, -v32, v35, v34
	v_fmac_f32_e32 v35, v36, v33
	v_fma_f32 v32, -v32, v35, v34
	v_div_fmas_f32 v32, v32, v33, v35
	v_div_fixup_f32 v34, v32, v214, 1.0
	v_mul_f32_e32 v0, v0, v34
	v_mul_f32_e32 v1, v1, v34
	v_cvt_pk_bf16_f32 v0, v0, v1
	v_mul_f32_e32 v1, v2, v34
	v_mad_i64_i32 v[32:33], s[68:69], v213, s65, v[116:117]
	v_and_b32_e32 v36, 63, v251
	v_and_b32_e32 v35, 31, v251
	v_lshrrev_b32_e32 v37, 5, v36
	v_lshlrev_b32_e32 v37, 3, v37
	s_movk_i32 s58, 0x90
	v_mad_u32_u24 v35, v35, s58, v37
	s_movk_i32 s59, 0x1200
	v_mad_u32_u24 v35, v254, s59, v35
	v_add_u32_e32 v35, 0x12000, v35
	v_lshrrev_b32_e32 v37, 3, v36
	v_and_b32_e32 v40, 7, v36
	v_lshlrev_b32_e32 v40, 4, v40
	v_mad_u32_u24 v36, v37, s58, v40
	v_mad_u32_u24 v36, v254, s59, v36
	v_add_u32_e32 v36, 0x12000, v36
	s_movk_i32 s58, 0xc00
	v_mad_u32_u24 v37, v37, s58, v40
	v_readfirstlane_b32 s56, v32
	v_readfirstlane_b32 s57, v33
	v_mul_f32_e32 v2, v3, v34
	v_cvt_pk_bf16_f32 v1, v1, v2
	ds_write_b64 v35, v[0:1]
	v_mul_f32_e32 v0, v4, v34
	v_mul_f32_e32 v1, v5, v34
	v_cvt_pk_bf16_f32 v0, v0, v1
	v_mul_f32_e32 v1, v6, v34
	v_mul_f32_e32 v2, v7, v34
	v_cvt_pk_bf16_f32 v1, v1, v2
	ds_write_b64 v35, v[0:1] offset:16
	v_mul_f32_e32 v0, v8, v34
	v_mul_f32_e32 v1, v9, v34
	v_cvt_pk_bf16_f32 v0, v0, v1
	v_mul_f32_e32 v1, v10, v34
	v_mul_f32_e32 v2, v11, v34
	v_cvt_pk_bf16_f32 v1, v1, v2
	ds_write_b64 v35, v[0:1] offset:32
	v_mul_f32_e32 v0, v12, v34
	v_mul_f32_e32 v1, v13, v34
	v_cvt_pk_bf16_f32 v0, v0, v1
	v_mul_f32_e32 v1, v14, v34
	v_mul_f32_e32 v2, v15, v34
	v_cvt_pk_bf16_f32 v1, v1, v2
	ds_write_b64 v35, v[0:1] offset:48
	v_mul_f32_e32 v0, v16, v34
	v_mul_f32_e32 v1, v17, v34
	v_cvt_pk_bf16_f32 v0, v0, v1
	v_mul_f32_e32 v1, v18, v34
	v_mul_f32_e32 v2, v19, v34
	v_cvt_pk_bf16_f32 v1, v1, v2
	ds_write_b64 v35, v[0:1] offset:64
	v_mul_f32_e32 v0, v20, v34
	v_mul_f32_e32 v1, v21, v34
	v_cvt_pk_bf16_f32 v0, v0, v1
	v_mul_f32_e32 v1, v22, v34
	v_mul_f32_e32 v2, v23, v34
	v_cvt_pk_bf16_f32 v1, v1, v2
	ds_write_b64 v35, v[0:1] offset:80
	v_mul_f32_e32 v0, v24, v34
	v_mul_f32_e32 v1, v25, v34
	v_cvt_pk_bf16_f32 v0, v0, v1
	v_mul_f32_e32 v1, v26, v34
	v_mul_f32_e32 v2, v27, v34
	v_cvt_pk_bf16_f32 v1, v1, v2
	ds_write_b64 v35, v[0:1] offset:96
	v_mul_f32_e32 v0, v28, v34
	v_mul_f32_e32 v1, v29, v34
	v_cvt_pk_bf16_f32 v0, v0, v1
	v_mul_f32_e32 v1, v30, v34
	v_mul_f32_e32 v2, v31, v34
	v_cvt_pk_bf16_f32 v1, v1, v2
	ds_write_b64 v35, v[0:1] offset:112
	s_waitcnt lgkmcnt(0)
	ds_read_b128 v[0:3], v36
	ds_read_b128 v[4:7], v36 offset:1152
	ds_read_b128 v[8:11], v36 offset:2304
	ds_read_b128 v[12:15], v36 offset:3456
	s_waitcnt lgkmcnt(3)
	global_store_dwordx4 v37, v[0:3], s[56:57]
	s_add_u32 s56, s56, 0x6000
	s_addc_u32 s57, s57, 0
	s_waitcnt lgkmcnt(2)
	global_store_dwordx4 v37, v[4:7], s[56:57]
	s_add_u32 s56, s56, 0x6000
	s_addc_u32 s57, s57, 0
	s_waitcnt lgkmcnt(1)
	global_store_dwordx4 v37, v[8:11], s[56:57]
	s_add_u32 s56, s56, 0x6000
	s_addc_u32 s57, s57, 0
	s_waitcnt lgkmcnt(0)
	global_store_dwordx4 v37, v[12:15], s[56:57]
	s_nop 1
	ds_read_b128 v[0:3], v243 offset:16
	s_nop 0
	ds_read_b128 v[16:19], v243
	ds_read_b128 v[4:7], v243 offset:144
	ds_read_b128 v[20:23], v243 offset:128
	v_lshlrev_b32_e32 v28, 5, v118
	v_or_b32_e32 v8, v28, v126
	v_lshlrev_b32_e32 v29, 2, v8
	ds_read_b128 v[8:11], v252 offset:6144
	ds_read_b128 v[24:27], v252 offset:2048
	ds_read_b128 v[12:15], v252 offset:24192
	ds_read_b128 v[44:47], v252 offset:20096
	v_or_b32_e32 v28, v28, v127
	v_lshlrev_b32_e32 v119, 2, v28
	v_lshlrev_b32_e32 v30, 16, v115
	v_and_b32_e32 v28, 0xffff0000, v115
	v_mov_b32_e32 v32, v28
	v_mov_b32_e32 v33, v30
	v_pk_mul_f32 v[48:49], v[32:33], v[32:33]
	v_lshlrev_b32_e32 v34, 16, v114
	v_and_b32_e32 v32, 0xffff0000, v114
	v_mov_b32_e32 v36, v32
	v_mov_b32_e32 v37, v34
	v_pk_mul_f32 v[50:51], v[36:37], v[36:37]
	v_and_b32_e32 v36, 0xffff0000, v113
	v_mov_b32_e32 v40, v36
	v_and_b32_e32 v113, 0xffff0000, v101
	v_and_b32_e32 v101, 0xffff0000, v100
	v_and_b32_e32 v100, 0xffff0000, v104
	v_pk_mul_f32 v[52:53], v[40:41], v[40:41]
	v_and_b32_e32 v40, 0xffff0000, v112
	v_and_b32_e32 v112, 0xffff0000, v105
	v_pk_mul_f32 v[104:105], v[100:101], v[100:101]
	v_pk_mul_f32 v[114:115], v[112:113], v[112:113]
	v_and_b32_e32 v41, 0xffff0000, v108
	v_pk_mul_f32 v[56:57], v[40:41], v[40:41]
	v_and_b32_e32 v37, 0xffff0000, v109
	v_lshlrev_b32_e32 v35, 16, v110
	v_and_b32_e32 v33, 0xffff0000, v110
	v_lshlrev_b32_e32 v31, 16, v111
	v_and_b32_e32 v29, 0xffff0000, v111
	s_andn2_b64 vcc, exec, s[78:79]
	s_waitcnt lgkmcnt(0)
	v_mov_b32_e32 v75, v0
	v_add_f32_e32 v0, v157, v105
	v_add_f32_e32 v0, v107, v0
	v_add_f32_e32 v0, v115, v0
	v_add_f32_e32 v0, v73, v0
	v_add_f32_e32 v0, v99, v0
	v_add_f32_e32 v0, v61, v0
	v_add_f32_e32 v0, v69, v0
	v_add_f32_e32 v0, v55, v0
	v_add_f32_e32 v0, v57, v0
	v_fmac_f32_e32 v0, v39, v39
	v_fmac_f32_e32 v0, v37, v37
	v_fmac_f32_e32 v0, v35, v35
	v_fmac_f32_e32 v0, v33, v33
	v_fmac_f32_e32 v0, v31, v31
	v_fmac_f32_e32 v0, v29, v29
	v_add_f32_e32 v0, v156, v0
	v_add_f32_e32 v0, v104, v0
	v_add_f32_e32 v0, v106, v0
	v_add_f32_e32 v0, v114, v0
	v_add_f32_e32 v0, v72, v0
	v_add_f32_e32 v0, v98, v0
	v_add_f32_e32 v0, v60, v0
	v_add_f32_e32 v0, v68, v0
	v_add_f32_e32 v0, v54, v0
	v_add_f32_e32 v0, v56, v0
	v_add_f32_e32 v0, v53, v0
	v_add_f32_e32 v0, v52, v0
	v_add_f32_e32 v0, v51, v0
	v_add_f32_e32 v0, v50, v0
	v_add_f32_e32 v0, v49, v0
	v_add_f32_e32 v0, v48, v0
	v_mov_b32_e32 v63, v2
	ds_bpermute_b32 v2, v188, v0
	s_waitcnt lgkmcnt(0)
	v_mov_b32_e32 v74, v4
	s_waitcnt lgkmcnt(0)
	v_mov_b32_e32 v158, v20
	s_waitcnt lgkmcnt(0)
	v_mov_b32_e32 v159, v16
	v_mov_b32_e32 v160, v24
	s_waitcnt lgkmcnt(0)
	v_add_f32_e32 v0, v0, v2
	v_fmamk_f32 v0, v0, 0x3c800000, v189
	v_rsq_f32_e32 v0, v0
	v_mov_b32_e32 v161, v44
	v_mov_b32_e32 v50, v44
	v_mov_b32_e32 v51, v24
	v_mul_f32_e32 v4, 0x3e38aa3b, v0
	v_pk_mul_f32 v[48:49], v[4:5], v[154:155] op_sel_hi:[0,1]
	v_pk_mul_f32 v[48:49], v[158:159], v[48:49]
	v_mov_b32_e32 v108, v22
	v_pk_mul_f32 v[50:51], v[50:51], v[48:49]
	v_pk_mul_f32 v[48:49], v[160:161], v[48:49]
	v_mov_b32_e32 v16, v21
	v_add_f32_e32 v22, v48, v49
	v_pk_mul_f32 v[48:49], v[4:5], v[100:101] op_sel_hi:[0,1]
	v_pk_mul_f32 v[16:17], v[16:17], v[48:49]
	v_mov_b32_e32 v24, v45
	v_mov_b32_e32 v44, v25
	v_pk_mul_f32 v[20:21], v[24:25], v[16:17]
	v_pk_mul_f32 v[16:17], v[44:45], v[16:17]
	v_mov_b32_e32 v109, v18
	v_add_f32_e32 v25, v16, v17
	v_pk_mul_f32 v[16:17], v[4:5], v[102:103] op_sel_hi:[0,1]
	v_mov_b32_e32 v110, v26
	v_mov_b32_e32 v111, v46
	v_sub_f32_e32 v24, v21, v20
	v_pk_mul_f32 v[16:17], v[16:17], v[108:109]
	v_mov_b32_e32 v20, v46
	v_mov_b32_e32 v21, v26
	v_pk_mul_f32 v[20:21], v[16:17], v[20:21]
	v_pk_mul_f32 v[16:17], v[16:17], v[110:111]
	v_sub_f32_e32 v20, v21, v20
	v_add_f32_e32 v21, v16, v17
	v_pk_mul_f32 v[16:17], v[4:5], v[112:113] op_sel_hi:[0,1]
	v_mov_b32_e32 v18, v23
	v_pk_mul_f32 v[16:17], v[16:17], v[18:19]
	v_mov_b32_e32 v26, v47
	v_mov_b32_e32 v46, v27
	v_pk_mul_f32 v[18:19], v[16:17], v[26:27]
	v_pk_mul_f32 v[16:17], v[16:17], v[46:47]
	v_mov_b32_e32 v76, v8
	v_add_f32_e32 v26, v16, v17
	v_pk_mul_f32 v[16:17], v[4:5], v[70:71] op_sel_hi:[0,1]
	v_mov_b32_e32 v77, v12
	v_sub_f32_e32 v23, v19, v18
	v_pk_mul_f32 v[16:17], v[16:17], v[74:75]
	v_mov_b32_e32 v18, v12
	v_mov_b32_e32 v19, v8
	v_pk_mul_f32 v[18:19], v[16:17], v[18:19]
	v_pk_mul_f32 v[16:17], v[16:17], v[76:77]
	v_sub_f32_e32 v18, v19, v18
	v_add_f32_e32 v19, v16, v17
	v_pk_mul_f32 v[16:17], v[4:5], v[78:79] op_sel_hi:[0,1]
	v_mov_b32_e32 v0, v5
	v_pk_mul_f32 v[0:1], v[16:17], v[0:1]
	v_mov_b32_e32 v8, v13
	v_pk_mul_f32 v[16:17], v[0:1], v[8:9]
	v_mov_b32_e32 v12, v9
	v_sub_f32_e32 v5, v17, v16
	v_pk_mul_f32 v[0:1], v[0:1], v[12:13]
	v_mov_b32_e32 v62, v6
	v_add_f32_e32 v12, v0, v1
	v_pk_mul_f32 v[0:1], v[4:5], v[58:59] op_sel_hi:[0,1]
	v_mov_b32_e32 v64, v10
	v_mov_b32_e32 v65, v14
	v_pk_mul_f32 v[0:1], v[0:1], v[62:63]
	v_mov_b32_e32 v8, v14
	v_mov_b32_e32 v9, v10
	v_pk_mul_f32 v[8:9], v[0:1], v[8:9]
	v_pk_mul_f32 v[0:1], v[0:1], v[64:65]
	v_sub_f32_e32 v8, v9, v8
	v_add_f32_e32 v9, v0, v1
	v_pk_mul_f32 v[0:1], v[4:5], v[66:67] op_sel_hi:[0,1]
	v_mov_b32_e32 v2, v7
	v_pk_mul_f32 v[0:1], v[0:1], v[2:3]
	v_mov_b32_e32 v10, v15
	v_mov_b32_e32 v14, v11
	v_pk_mul_f32 v[2:3], v[0:1], v[10:11]
	v_pk_mul_f32 v[0:1], v[0:1], v[14:15]
	v_sub_f32_e32 v6, v51, v50
	v_sub_f32_e32 v2, v3, v2
	v_add_f32_e32 v0, v0, v1
	v_cvt_pk_bf16_f32 v48, v6, v24
	v_cvt_pk_bf16_f32 v49, v20, v23
	v_cvt_pk_bf16_f32 v50, v18, v5
	v_cvt_pk_bf16_f32 v51, v8, v2
	v_cvt_pk_bf16_f32 v98, v22, v25
	v_cvt_pk_bf16_f32 v99, v21, v26
	v_cvt_pk_bf16_f32 v100, v19, v12
	v_cvt_pk_bf16_f32 v101, v9, v0
	ds_read_b128 v[0:3], v243 offset:80
	ds_read_b128 v[6:9], v243 offset:64
	ds_read_b128 v[10:13], v243 offset:208
	ds_read_b128 v[14:17], v243 offset:192
	v_pk_mul_f32 v[18:19], v[4:5], v[42:43] op_sel_hi:[0,1]
	s_waitcnt lgkmcnt(0)
	v_mov_b32_e32 v21, v6
	s_waitcnt lgkmcnt(0)
	v_mov_b32_e32 v20, v14
	v_pk_mul_f32 v[26:27], v[18:19], v[20:21]
	ds_read_b128 v[18:21], v252 offset:14336
	ds_read_b128 v[22:25], v252 offset:10240
	ds_read_b128 v[42:45], v252 offset:32384
	ds_read_b128 v[52:55], v252 offset:28288
	v_mov_b32_e32 v6, v15
	s_waitcnt lgkmcnt(0)
	v_mov_b32_e32 v47, v22
	s_waitcnt lgkmcnt(0)
	v_mov_b32_e32 v46, v52
	v_pk_mul_f32 v[46:47], v[26:27], v[46:47]
	s_nop 0
	v_sub_f32_e32 v5, v47, v46
	v_mov_b32_e32 v46, v22
	v_mov_b32_e32 v47, v52
	v_pk_mul_f32 v[26:27], v[26:27], v[46:47]
	v_mov_b32_e32 v22, v53
	v_add_f32_e32 v46, v26, v27
	v_pk_mul_f32 v[26:27], v[4:5], v[40:41] op_sel_hi:[0,1]
	v_pk_mul_f32 v[6:7], v[26:27], v[6:7]
	v_mov_b32_e32 v52, v23
	v_pk_mul_f32 v[14:15], v[6:7], v[22:23]
	v_pk_mul_f32 v[6:7], v[6:7], v[52:53]
	v_sub_f32_e32 v22, v15, v14
	v_add_f32_e32 v23, v6, v7
	v_pk_mul_f32 v[6:7], v[4:5], v[38:39] op_sel_hi:[0,1]
	v_mov_b32_e32 v14, v16
	v_mov_b32_e32 v15, v8
	v_pk_mul_f32 v[6:7], v[6:7], v[14:15]
	v_mov_b32_e32 v14, v54
	v_mov_b32_e32 v15, v24
	v_pk_mul_f32 v[14:15], v[6:7], v[14:15]
	v_mov_b32_e32 v8, v17
	v_sub_f32_e32 v16, v15, v14
	v_mov_b32_e32 v14, v24
	v_mov_b32_e32 v15, v54
	v_pk_mul_f32 v[6:7], v[6:7], v[14:15]
	v_mov_b32_e32 v24, v55
	v_add_f32_e32 v14, v6, v7
	v_pk_mul_f32 v[6:7], v[4:5], v[36:37] op_sel_hi:[0,1]
	v_pk_mul_f32 v[6:7], v[6:7], v[8:9]
	v_mov_b32_e32 v54, v25
	v_pk_mul_f32 v[8:9], v[6:7], v[24:25]
	v_pk_mul_f32 v[6:7], v[6:7], v[54:55]
	v_sub_f32_e32 v15, v9, v8
	v_add_f32_e32 v17, v6, v7
	v_pk_mul_f32 v[6:7], v[4:5], v[34:35] op_sel_hi:[0,1]
	s_waitcnt lgkmcnt(0)
	v_mov_b32_e32 v8, v10
	s_waitcnt lgkmcnt(0)
	v_mov_b32_e32 v9, v0
	v_pk_mul_f32 v[6:7], v[6:7], v[8:9]
	v_mov_b32_e32 v8, v42
	v_mov_b32_e32 v9, v18
	v_pk_mul_f32 v[8:9], v[6:7], v[8:9]
	v_mov_b32_e32 v0, v11
	v_sub_f32_e32 v10, v9, v8
	v_mov_b32_e32 v8, v18
	v_mov_b32_e32 v9, v42
	v_pk_mul_f32 v[6:7], v[6:7], v[8:9]
	v_mov_b32_e32 v18, v43
	v_add_f32_e32 v8, v6, v7
	v_pk_mul_f32 v[6:7], v[4:5], v[32:33] op_sel_hi:[0,1]
	v_pk_mul_f32 v[0:1], v[6:7], v[0:1]
	v_mov_b32_e32 v42, v19
	v_pk_mul_f32 v[6:7], v[0:1], v[18:19]
	v_pk_mul_f32 v[0:1], v[0:1], v[42:43]
	v_sub_f32_e32 v9, v7, v6
	v_add_f32_e32 v11, v0, v1
	v_pk_mul_f32 v[0:1], v[4:5], v[30:31] op_sel_hi:[0,1]
	v_mov_b32_e32 v6, v12
	v_mov_b32_e32 v7, v2
	v_pk_mul_f32 v[0:1], v[0:1], v[6:7]
	v_mov_b32_e32 v6, v44
	v_mov_b32_e32 v7, v20
	v_pk_mul_f32 v[6:7], v[0:1], v[6:7]
	v_mov_b32_e32 v2, v13
	v_sub_f32_e32 v12, v7, v6
	v_mov_b32_e32 v6, v20
	v_mov_b32_e32 v7, v44
	v_pk_mul_f32 v[0:1], v[0:1], v[6:7]
	v_mov_b32_e32 v20, v45
	v_add_f32_e32 v6, v0, v1
	v_pk_mul_f32 v[0:1], v[4:5], v[28:29] op_sel_hi:[0,1]
	v_pk_mul_f32 v[0:1], v[0:1], v[2:3]
	v_mov_b32_e32 v44, v21
	v_pk_mul_f32 v[2:3], v[0:1], v[20:21]
	v_pk_mul_f32 v[0:1], v[0:1], v[44:45]
	v_sub_f32_e32 v2, v3, v2
	v_add_f32_e32 v0, v0, v1
	v_cvt_pk_bf16_f32 v102, v5, v22
	v_cvt_pk_bf16_f32 v103, v16, v15
	v_cvt_pk_bf16_f32 v104, v10, v9
	v_cvt_pk_bf16_f32 v105, v12, v2
	v_cvt_pk_bf16_f32 v106, v46, v23
	v_cvt_pk_bf16_f32 v107, v14, v17
	v_cvt_pk_bf16_f32 v108, v8, v11
	v_cvt_pk_bf16_f32 v109, v6, v0
	ds_read_b128 v[0:3], v202
	ds_read_b128 v[4:7], v202 offset:32
	s_waitcnt lgkmcnt(1)
	v_mfma_f32_32x32x16_bf16 v[64:79], v[0:3], v[48:51], 0
	ds_read_b128 v[0:3], v202 offset:64
	s_waitcnt lgkmcnt(1)
	v_mfma_f32_32x32x16_bf16 v[64:79], v[4:7], v[102:105], v[64:79]
	s_waitcnt lgkmcnt(0)
	v_mfma_f32_32x32x16_bf16 v[64:79], v[0:3], v[98:101], v[64:79]
	ds_read_b128 v[0:3], v202 offset:96
	s_waitcnt lgkmcnt(0)
	v_mfma_f32_32x32x16_bf16 v[64:79], v[0:3], v[106:109], v[64:79]
	ds_read_b128 v[0:3], v203
	ds_read_b128 v[4:7], v203 offset:32
	s_waitcnt lgkmcnt(1)
	v_mfma_f32_32x32x16_bf16 v[32:47], v[0:3], v[48:51], 0
	ds_read_b128 v[0:3], v203 offset:64
	s_waitcnt lgkmcnt(1)
	v_mfma_f32_32x32x16_bf16 v[32:47], v[4:7], v[102:105], v[32:47]
	s_waitcnt lgkmcnt(0)
	v_mfma_f32_32x32x16_bf16 v[32:47], v[0:3], v[98:101], v[32:47]
	ds_read_b128 v[0:3], v203 offset:96
	s_waitcnt lgkmcnt(0)
	v_mfma_f32_32x32x16_bf16 v[32:47], v[0:3], v[106:109], v[32:47]
	ds_read_b128 v[0:3], v204
	ds_read_b128 v[4:7], v204 offset:32
	s_waitcnt lgkmcnt(1)
	v_mfma_f32_32x32x16_bf16 v[16:31], v[0:3], v[48:51], 0
	ds_read_b128 v[0:3], v204 offset:64
	s_waitcnt lgkmcnt(1)
	v_mfma_f32_32x32x16_bf16 v[16:31], v[4:7], v[102:105], v[16:31]
	s_waitcnt lgkmcnt(0)
	v_mfma_f32_32x32x16_bf16 v[16:31], v[0:3], v[98:101], v[16:31]
	ds_read_b128 v[0:3], v204 offset:96
	s_waitcnt lgkmcnt(0)
	v_mfma_f32_32x32x16_bf16 v[16:31], v[0:3], v[106:109], v[16:31]
	ds_read_b128 v[0:3], v205
	ds_read_b128 v[52:55], v205 offset:32
	s_waitcnt lgkmcnt(1)
	v_mfma_f32_32x32x16_bf16 v[0:15], v[0:3], v[48:51], 0
	s_waitcnt lgkmcnt(0)
	v_mfma_f32_32x32x16_bf16 v[0:15], v[52:55], v[102:105], v[0:15]
	ds_read_b128 v[52:55], v205 offset:64
	s_waitcnt lgkmcnt(0)
	v_mfma_f32_32x32x16_bf16 v[0:15], v[52:55], v[98:101], v[0:15]
	ds_read_b128 v[52:55], v205 offset:96
	s_waitcnt lgkmcnt(0)
	v_mfma_f32_32x32x16_bf16 v[0:15], v[52:55], v[106:109], v[0:15]
	ds_read_b128 v[52:55], v206
	ds_read_b128 v[110:113], v206 offset:32
	s_waitcnt lgkmcnt(1)
	v_mfma_f32_32x32x16_bf16 v[48:63], v[52:55], v[48:51], 0
	s_waitcnt lgkmcnt(0)
	v_mfma_f32_32x32x16_bf16 v[48:63], v[110:113], v[102:105], v[48:63]
	ds_read_b128 v[102:105], v206 offset:64
	s_waitcnt lgkmcnt(0)
	v_mfma_f32_32x32x16_bf16 v[48:63], v[102:105], v[98:101], v[48:63]
	ds_read_b128 v[98:101], v206 offset:96
	s_waitcnt lgkmcnt(0)
	v_mfma_f32_32x32x16_bf16 v[48:63], v[98:101], v[106:109], v[48:63]
	s_cbranch_vccz .LBB0_346
	v_cndmask_b32_e64 v98, v212, v64, s[2:3]
	v_cndmask_b32_e64 v105, v65, v212, s[4:5]
	v_cndmask_b32_e64 v104, v212, v66, s[6:7]
	v_cndmask_b32_e64 v103, v212, v67, s[8:9]
	v_cndmask_b32_e64 v102, v212, v68, s[10:11]
	v_cndmask_b32_e64 v101, v212, v69, s[12:13]
	v_cndmask_b32_e64 v100, v212, v70, s[14:15]
	v_cndmask_b32_e64 v99, v212, v71, s[16:17]
	v_cndmask_b32_e64 v71, v212, v72, s[18:19]
	v_cndmask_b32_e64 v70, v212, v73, s[20:21]
	v_cndmask_b32_e64 v69, v212, v74, s[22:23]
	v_cndmask_b32_e64 v68, v212, v75, s[24:25]
	v_cndmask_b32_e64 v67, v212, v76, s[26:27]
	v_cndmask_b32_e64 v66, v212, v77, s[28:29]
	v_cndmask_b32_e64 v65, v212, v78, s[30:31]
	v_cndmask_b32_e64 v64, v212, v79, s[34:35]
	s_branch .LBB0_347
